# write-through (sc1) epilogue stores also in the EpiRes and EpiPle GEMM instances
# baseline (speedup 1.0000x reference)
; #define EP_LOAD(q) do { _Pragma("unroll") for (int bj = 0; bj < 2; ++bj) { const unsigned o = ER_OFF(q, bj); t[(q) & 1][bj] = *(const u32x4*)(base + o); pw[(q) & 1][bj] = *(const u32x4*)(pp + o); } } while (0)
; __device__ __forceinline__ void load_rstd(float (&rsv)[2][4], const ssq_t* ssq, int row0) {
;     ssq_t t[2][4];
; #pragma unroll
;     for (int ai = 0; ai < 2; ++ai)
; #pragma unroll
;         for (int m = 0; m < 4; ++m) t[ai][m] = ssq[row0 + ai * HALF + m * 16];
; #pragma unroll
;     for (int ai = 0; ai < 2; ++ai)
; #pragma unroll
;         for (int m = 0; m < 4; ++m) rsv[ai][m] = __builtin_amdgcn_rsqf((float)t[ai][m] * (SSQ_INV / 1024.0f) + 1e-6f);
;     __device__ __forceinline__ void operator()(f32x4 (&acc)[2][2][4][2], const Unit& u, int wr, int wc, int fr, int fq) const {
;         const int row0 = u.pm * BM + wr * 64 + fr, col0 = u.pn * BM + wc * 32 + 8 * fq; const unsigned off0 = (unsigned)row0 * 1024u + (unsigned)col0;
;         float rsv[2][4]; load_rstd(rsv, ssq, row0);
;         u32x4 t[2][2], pw[2][2];
;     ...
;         bf16_t* hb = pp;
;         EP_LOAD(0); EP_LOAD(1); EP_ADD(0); EP_ADD(1);
; #pragma unroll
;         for (int q = 0; q < 8; q += 2) { if (q < 6) { EP_LOAD(q + 2); EP_LOAD(q + 3); } ER_STORE(q); ER_STORE(q + 1); if (q < 6) { EP_ADD(q + 2); EP_ADD(q + 3); } }
.LBB0_238:
	v_mov_b32_e32 v128, v170
	s_lshl_b32 s13, s69, 8
	v_readfirstlane_b32 s12, v128
	s_ashr_i32 s46, s12, 2
	s_andn2_b32 s46, s46, 63
	s_lshr_b32 s12, s12, 1
	s_add_i32 s46, s46, s13
	s_lshl_b32 s13, s68, 8
	s_and_b32 s12, s12, 0x60
	v_bfe_u32 v199, v128, 4, 2
	v_and_or_b32 v192, v128, 15, s46
	s_or_b32 s12, s12, s13
	v_lshl_or_b32 v128, v199, 3, s12
	v_ashrrev_i32_e32 v193, 31, v192
	v_lshl_add_u32 v190, v192, 10, v128
	v_lshl_add_u64 v[128:129], v[192:193], 3, s[26:27]
	global_load_dwordx2 v[130:131], v[128:129], off
	global_load_dwordx2 v[212:213], v[128:129], off offset:128
	global_load_dwordx2 v[202:203], v[128:129], off offset:256
	global_load_dwordx2 v[196:197], v[128:129], off offset:384
	global_load_dwordx2 v[194:195], v[128:129], off offset:1024
	global_load_dwordx2 v[188:189], v[128:129], off offset:1152
	global_load_dwordx2 v[186:187], v[128:129], off offset:1280
	global_load_dwordx2 v[166:167], v[128:129], off offset:1408
	v_mov_b32_e32 v191, v169
	v_add_u32_e32 v168, 0x4000, v190
	v_cmp_eq_u32_e32 vcc, 0, v199
	v_cmp_lt_i32_e64 s[12:13], v233, v228
	v_lshl_add_u64 v[192:193], v[192:193], 3, s[40:41]
	s_waitcnt vmcnt(0)
	v_ffbh_u32_e32 v128, v131
	v_min_u32_e32 v132, 32, v128
	v_lshlrev_b64 v[128:129], v132, v[130:131]
	v_min_u32_e32 v128, 1, v128
	v_or_b32_e32 v128, v129, v128
	v_cvt_f32_u32_e32 v128, v128
	v_sub_u32_e32 v129, 32, v132
	v_ldexp_f32 v128, v128, v129
	v_fmamk_f32 v128, v128, 0x30800000, v223
	v_rsq_f32_e32 v198, v128
	v_lshlrev_b64 v[128:129], 1, v[190:191]
	v_lshl_add_u64 v[130:131], s[70:71], 0, v[128:129]
	global_load_dwordx4 v[152:155], v[130:131], off
	v_lshl_add_u64 v[214:215], s[20:21], 0, v[128:129]
	global_load_dwordx4 v[156:159], v[214:215], off
	global_load_dwordx4 v[144:147], v[130:131], off offset:256
	global_load_dwordx4 v[148:151], v[214:215], off offset:256
	v_pk_mul_f32 v[200:201], v[120:121], v[198:199] op_sel_hi:[1,0]
	v_pk_mul_f32 v[120:121], v[126:127], v[198:199] op_sel_hi:[1,0]
	v_mul_f32_e32 v127, 0xbfb8aa3b, v200
	v_exp_f32_e32 v127, v127
	v_pk_mul_f32 v[122:123], v[122:123], v[198:199] op_sel_hi:[1,0]
	v_pk_mul_f32 v[124:125], v[124:125], v[198:199] op_sel_hi:[1,0]
	v_mul_f32_e32 v122, 0xbfb8aa3b, v122
	v_add_f32_e32 v127, 1.0, v127
	v_rcp_f32_e32 v127, v127
	v_exp_f32_e32 v122, v122
	v_mul_f32_e32 v123, 0xbfb8aa3b, v123
	v_exp_f32_e32 v123, v123
	v_mul_f32_e32 v120, 0xbfb8aa3b, v120
	v_add_f32_e32 v122, 1.0, v122
	v_rcp_f32_e32 v122, v122
	v_add_f32_e32 v123, 1.0, v123
	v_rcp_f32_e32 v123, v123
	v_exp_f32_e32 v120, v120
	v_mul_f32_e32 v121, 0xbfb8aa3b, v121
	v_pk_mul_f32 v[116:117], v[116:117], v[198:199] op_sel_hi:[1,0]
	v_exp_f32_e32 v121, v121
	v_mul_f32_e32 v116, 0xbfb8aa3b, v116
	v_exp_f32_e32 v116, v116
	v_mul_f32_e32 v117, 0xbfb8aa3b, v117
	v_exp_f32_e32 v117, v117
	v_add_f32_e32 v120, 1.0, v120
	v_rcp_f32_e32 v120, v120
	v_add_f32_e32 v121, 1.0, v121
	v_rcp_f32_e32 v121, v121
	v_add_f32_e32 v116, 1.0, v116
	v_rcp_f32_e32 v116, v116
	v_add_f32_e32 v117, 1.0, v117
	v_rcp_f32_e32 v117, v117
	v_pk_mul_f32 v[118:119], v[118:119], v[198:199] op_sel_hi:[1,0]
	v_pk_mul_f32 v[112:113], v[112:113], v[198:199] op_sel_hi:[1,0]
	v_pk_mul_f32 v[114:115], v[114:115], v[198:199] op_sel_hi:[1,0]
	v_mul_f32_e32 v112, 0xbfb8aa3b, v112
	v_exp_f32_e32 v112, v112
	v_mul_f32_e32 v113, 0xbfb8aa3b, v113
	v_exp_f32_e32 v113, v113
	v_lshlrev_b64 v[128:129], 1, v[168:169]
	v_add_f32_e32 v112, 1.0, v112
	v_rcp_f32_e32 v112, v112
	v_add_f32_e32 v113, 1.0, v113
	v_rcp_f32_e32 v113, v113
	v_add_u32_e32 v168, 0x4080, v190
	v_lshlrev_b64 v[132:133], 1, v[168:169]
	v_add_u32_e32 v168, 0x8000, v190
	v_lshl_add_u64 v[130:131], s[70:71], 0, v[128:129]
	global_load_dwordx4 v[136:139], v[130:131], off
	v_lshl_add_u64 v[210:211], s[20:21], 0, v[128:129]
	v_lshl_add_u64 v[128:129], s[70:71], 0, v[132:133]
	v_lshl_add_u64 v[206:207], s[20:21], 0, v[132:133]
	global_load_dwordx4 v[140:143], v[210:211], off
	global_load_dwordx4 v[132:135], v[206:207], off
	s_waitcnt vmcnt(5)
	v_lshlrev_b32_e32 v126, 16, v156
	v_lshlrev_b32_e32 v191, 16, v152
	v_fmac_f32_e32 v191, v127, v126
	v_mul_f32_e32 v127, 0xbfb8aa3b, v201
	v_exp_f32_e32 v127, v127
	v_and_b32_e32 v220, 0xffff0000, v152
	v_and_b32_e32 v126, 0xffff0000, v156
	v_lshlrev_b32_e32 v221, 16, v153
	v_add_f32_e32 v127, 1.0, v127
	v_rcp_f32_e32 v127, v127
	v_and_b32_e32 v239, 0xffff0000, v153
	v_lshlrev_b32_e32 v240, 16, v154
	v_and_b32_e32 v241, 0xffff0000, v154
	v_fmac_f32_e32 v220, v127, v126
	v_lshlrev_b32_e32 v126, 16, v157
	v_fmac_f32_e32 v221, v122, v126
	v_and_b32_e32 v122, 0xffff0000, v157
	v_fmac_f32_e32 v239, v123, v122
	v_mul_f32_e32 v123, 0xbfb8aa3b, v124
	v_exp_f32_e32 v123, v123
	v_lshlrev_b32_e32 v122, 16, v158
	v_lshlrev_b32_e32 v242, 16, v155
	v_and_b32_e32 v243, 0xffff0000, v155
	v_add_f32_e32 v123, 1.0, v123
	v_rcp_f32_e32 v123, v123
	s_waitcnt vmcnt(4)
	v_lshlrev_b32_e32 v226, 16, v144
	v_and_b32_e32 v227, 0xffff0000, v144
	v_lshlrev_b32_e32 v237, 16, v145
	v_fmac_f32_e32 v240, v123, v122
	v_mul_f32_e32 v123, 0xbfb8aa3b, v125
	v_exp_f32_e32 v123, v123
	v_and_b32_e32 v122, 0xffff0000, v158
	v_and_b32_e32 v248, 0xffff0000, v145
	v_lshlrev_b32_e32 v249, 16, v146
	v_add_f32_e32 v123, 1.0, v123
	v_rcp_f32_e32 v123, v123
	v_and_b32_e32 v250, 0xffff0000, v146
	v_lshlrev_b32_e32 v251, 16, v147
	v_and_b32_e32 v252, 0xffff0000, v147
	v_fmac_f32_e32 v241, v123, v122
	v_lshlrev_b32_e32 v122, 16, v159
	v_fmac_f32_e32 v242, v120, v122
	v_and_b32_e32 v120, 0xffff0000, v159
	v_fmac_f32_e32 v243, v121, v120
	s_waitcnt vmcnt(3)
; #define EP_LOAD(q) do { _Pragma("unroll") for (int bj = 0; bj < 2; ++bj) { const unsigned o = ER_OFF(q, bj); t[(q) & 1][bj] = *(const u32x4*)(base + o); pw[(q) & 1][bj] = *(const u32x4*)(pp + o); } } while (0)
;     __device__ __forceinline__ void operator()(f32x4 (&acc)[2][2][4][2], const Unit& u, int wr, int wc, int fr, int fq) const {
;     ...
;         bf16_t* hb = pp;
;         EP_LOAD(0); EP_LOAD(1); EP_ADD(0); EP_ADD(1);
; #pragma unroll
;         for (int q = 0; q < 8; q += 2) { if (q < 6) { EP_LOAD(q + 2); EP_LOAD(q + 3); } ER_STORE(q); ER_STORE(q + 1); if (q < 6) { EP_ADD(q + 2); EP_ADD(q + 3); } }
	v_lshlrev_b32_e32 v120, 16, v148
	v_fmac_f32_e32 v226, v116, v120
	v_and_b32_e32 v116, 0xffff0000, v148
	v_fmac_f32_e32 v227, v117, v116
	v_mul_f32_e32 v117, 0xbfb8aa3b, v118
	v_exp_f32_e32 v117, v117
	v_lshlrev_b32_e32 v116, 16, v149
	v_add_f32_e32 v117, 1.0, v117
	v_rcp_f32_e32 v117, v117
	s_nop 0
	v_fmac_f32_e32 v237, v117, v116
	v_mul_f32_e32 v117, 0xbfb8aa3b, v119
	v_exp_f32_e32 v117, v117
	v_and_b32_e32 v116, 0xffff0000, v149
	v_add_f32_e32 v117, 1.0, v117
	v_rcp_f32_e32 v117, v117
	s_nop 0
	v_fmac_f32_e32 v248, v117, v116
	v_lshlrev_b32_e32 v116, 16, v150
	v_fmac_f32_e32 v249, v112, v116
	v_and_b32_e32 v112, 0xffff0000, v150
	v_fmac_f32_e32 v250, v113, v112
	v_mul_f32_e32 v113, 0xbfb8aa3b, v114
	v_exp_f32_e32 v113, v113
	v_lshlrev_b32_e32 v112, 16, v151
	v_add_f32_e32 v113, 1.0, v113
	v_rcp_f32_e32 v113, v113
	s_nop 0
	v_fmac_f32_e32 v251, v113, v112
	v_mul_f32_e32 v113, 0xbfb8aa3b, v115
	v_exp_f32_e32 v113, v113
	v_and_b32_e32 v112, 0xffff0000, v151
	v_add_f32_e32 v113, 1.0, v113
	v_rcp_f32_e32 v113, v113
	s_nop 0
	v_fmac_f32_e32 v252, v113, v112
	v_lshlrev_b64 v[112:113], 1, v[168:169]
	v_add_u32_e32 v168, 0x8080, v190
	v_lshl_add_u64 v[114:115], s[70:71], 0, v[112:113]
	v_lshl_add_u64 v[208:209], s[20:21], 0, v[112:113]
	v_lshlrev_b64 v[112:113], 1, v[168:169]
	v_add_u32_e32 v168, 0xc000, v190
	global_load_dwordx4 v[152:155], v[114:115], off
	v_lshl_add_u64 v[114:115], s[70:71], 0, v[112:113]
	v_lshl_add_u64 v[204:205], s[20:21], 0, v[112:113]
	v_lshlrev_b64 v[112:113], 1, v[168:169]
	v_add_u32_e32 v168, 0xc080, v190
	v_lshl_add_u64 v[200:201], s[20:21], 0, v[112:113]
	v_lshlrev_b64 v[116:117], 1, v[168:169]
	global_load_dwordx4 v[144:147], v[114:115], off
	global_load_dwordx4 v[124:127], v[200:201], off
	v_lshl_add_u64 v[114:115], s[70:71], 0, v[112:113]
	v_lshl_add_u64 v[112:113], s[70:71], 0, v[116:117]
	v_lshl_add_u64 v[198:199], s[20:21], 0, v[116:117]
	global_load_dwordx4 v[128:131], v[128:129], off
	s_nop 0
	global_load_dwordx4 v[156:159], v[208:209], off
	global_load_dwordx4 v[148:151], v[204:205], off
	global_load_dwordx4 v[120:123], v[114:115], off
	global_load_dwordx4 v[116:119], v[198:199], off
	s_nop 0
	global_load_dwordx4 v[112:115], v[112:113], off
	v_cvt_pk_bf16_f32 v244, v191, v220
	v_cvt_pk_bf16_f32 v245, v221, v239
	v_cvt_pk_bf16_f32 v246, v240, v241
	v_cvt_pk_bf16_f32 v247, v242, v243
	global_store_dwordx4 v[214:215], v[244:247], off sc1
	v_and_b32_e32 v191, 0xffff0000, v244
	v_lshlrev_b32_e32 v168, 16, v244
	v_mul_f32_e32 v191, v191, v191
	v_and_b32_e32 v220, 0xffff0000, v245
	v_fmac_f32_e32 v191, v168, v168
	v_lshlrev_b32_e32 v168, 16, v245
	v_mul_f32_e32 v220, v220, v220
	v_fmac_f32_e32 v220, v168, v168
	v_add_f32_e32 v168, v191, v220
	v_and_b32_e32 v220, 0xffff0000, v246
	v_lshlrev_b32_e32 v191, 16, v246
	v_mul_f32_e32 v220, v220, v220
	v_fmac_f32_e32 v220, v191, v191
	v_add_f32_e32 v168, v168, v220
	v_and_b32_e32 v220, 0xffff0000, v247
	v_lshlrev_b32_e32 v191, 16, v247
	v_mul_f32_e32 v220, v220, v220
	v_cvt_pk_bf16_f32 v240, v226, v227
	v_cvt_pk_bf16_f32 v241, v237, v248
	v_cvt_pk_bf16_f32 v242, v249, v250
	v_cvt_pk_bf16_f32 v243, v251, v252
	global_store_dwordx4 v[214:215], v[240:243], off offset:256 sc1
	v_and_b32_e32 v214, 0xffff0000, v240
	v_fmac_f32_e32 v220, v191, v191
	v_lshlrev_b32_e32 v191, 16, v240
	v_mul_f32_e32 v214, v214, v214
	v_add_f32_e32 v168, v168, v220
	v_fmac_f32_e32 v214, v191, v191
	v_add_f32_e32 v168, v168, v214
	v_and_b32_e32 v214, 0xffff0000, v241
	v_lshlrev_b32_e32 v191, 16, v241
	v_mul_f32_e32 v214, v214, v214
	v_fmac_f32_e32 v214, v191, v191
	v_add_f32_e32 v168, v168, v214
	v_and_b32_e32 v214, 0xffff0000, v242
	v_lshlrev_b32_e32 v191, 16, v242
	v_mul_f32_e32 v214, v214, v214
	v_fmac_f32_e32 v214, v191, v191
	v_add_f32_e32 v168, v168, v214
	v_and_b32_e32 v214, 0xffff0000, v243
	v_lshlrev_b32_e32 v191, 16, v243
	v_mul_f32_e32 v214, v214, v214
	v_fmac_f32_e32 v214, v191, v191
	v_cndmask_b32_e64 v191, v225, v233, s[12:13]
	v_add_f32_e32 v168, v168, v214
	v_lshlrev_b32_e32 v191, 2, v191
	ds_bpermute_b32 v214, v191, v168
	v_cmp_lt_i32_e64 s[12:13], v234, v228
	s_waitcnt lgkmcnt(0)
	v_add_f32_e32 v168, v168, v214
	v_cndmask_b32_e64 v214, v225, v234, s[12:13]
	v_lshlrev_b32_e32 v214, 2, v214
	ds_bpermute_b32 v215, v214, v168
	s_and_saveexec_b64 s[12:13], vcc
	s_cbranch_execz .LBB0_240
	s_waitcnt lgkmcnt(0)
	v_add_f32_e32 v168, v168, v215
	v_mul_f32_e32 v168, 0x49800000, v168
	v_trunc_f32_e32 v168, v168
	v_mul_f32_e32 v215, 0x2f800000, v168
	v_floor_f32_e32 v215, v215
	v_fmac_f32_e32 v168, 0xcf800000, v215
	v_cvt_u32_f32_e32 v220, v168
	v_cvt_u32_f32_e32 v221, v215
	global_atomic_add_x2 v[192:193], v[220:221], off
; #define EP_LOAD(q) do { _Pragma("unroll") for (int bj = 0; bj < 2; ++bj) { const unsigned o = ER_OFF(q, bj); t[(q) & 1][bj] = *(const u32x4*)(base + o); pw[(q) & 1][bj] = *(const u32x4*)(pp + o); } } while (0)
;     __device__ __forceinline__ void operator()(f32x4 (&acc)[2][2][4][2], const Unit& u, int wr, int wc, int fr, int fq) const {
;     ...
;         bf16_t* hb = pp;
;         EP_LOAD(0); EP_LOAD(1); EP_ADD(0); EP_ADD(1);
; #pragma unroll
;         for (int q = 0; q < 8; q += 2) { if (q < 6) { EP_LOAD(q + 2); EP_LOAD(q + 3); } ER_STORE(q); ER_STORE(q + 1); if (q < 6) { EP_ADD(q + 2); EP_ADD(q + 3); } }
.LBB0_240:
	s_or_b64 exec, exec, s[12:13]
	v_ffbh_u32_e32 v168, v213
	v_min_u32_e32 v168, 32, v168
	v_lshlrev_b64 v[212:213], v168, v[212:213]
	v_min_u32_e32 v212, 1, v212
	v_or_b32_e32 v212, v213, v212
	v_cvt_f32_u32_e32 v212, v212
	v_sub_u32_e32 v168, 32, v168
	s_waitcnt vmcnt(12)
	v_lshlrev_b32_e32 v213, 16, v140
	v_and_b32_e32 v140, 0xffff0000, v140
	v_ldexp_f32 v168, v212, v168
	v_fmamk_f32 v168, v168, 0x30800000, v223
	v_rsq_f32_e32 v168, v168
	v_lshlrev_b32_e32 v212, 16, v136
	v_and_b32_e32 v136, 0xffff0000, v136
	v_pk_mul_f32 v[108:109], v[108:109], v[168:169] op_sel_hi:[1,0]
	s_nop 0
	v_mul_f32_e32 v108, 0xbfb8aa3b, v108
	v_mul_f32_e32 v109, 0xbfb8aa3b, v109
	s_waitcnt lgkmcnt(0)
	v_exp_f32_e32 v215, v108
	v_exp_f32_e32 v220, v109
	v_pk_mul_f32 v[108:109], v[110:111], v[168:169] op_sel_hi:[1,0]
	v_pk_mul_f32 v[104:105], v[104:105], v[168:169] op_sel_hi:[1,0]
	v_mul_f32_e32 v108, 0xbfb8aa3b, v108
	v_exp_f32_e32 v108, v108
	v_mul_f32_e32 v109, 0xbfb8aa3b, v109
	v_exp_f32_e32 v109, v109
	v_mul_f32_e32 v104, 0xbfb8aa3b, v104
	v_exp_f32_e32 v104, v104
	v_mul_f32_e32 v105, 0xbfb8aa3b, v105
	v_add_f32_e32 v110, 1.0, v215
	v_add_f32_e32 v111, 1.0, v220
	v_exp_f32_e32 v105, v105
	v_rcp_f32_e32 v110, v110
	v_rcp_f32_e32 v111, v111
	v_add_f32_e32 v108, 1.0, v108
	v_rcp_f32_e32 v108, v108
	v_add_f32_e32 v109, 1.0, v109
	v_rcp_f32_e32 v109, v109
	v_add_f32_e32 v104, 1.0, v104
	v_rcp_f32_e32 v104, v104
	v_add_f32_e32 v105, 1.0, v105
	v_fmac_f32_e32 v212, v110, v213
	v_fmac_f32_e32 v136, v111, v140
	v_lshlrev_b32_e32 v110, 16, v137
	v_lshlrev_b32_e32 v111, 16, v141
	v_rcp_f32_e32 v105, v105
	v_fmac_f32_e32 v110, v108, v111
	v_and_b32_e32 v108, 0xffff0000, v137
	v_and_b32_e32 v111, 0xffff0000, v141
	v_fmac_f32_e32 v108, v109, v111
	v_lshlrev_b32_e32 v109, 16, v138
	v_lshlrev_b32_e32 v111, 16, v142
	v_pk_mul_f32 v[106:107], v[106:107], v[168:169] op_sel_hi:[1,0]
	v_fmac_f32_e32 v109, v104, v111
	v_and_b32_e32 v104, 0xffff0000, v138
	v_and_b32_e32 v111, 0xffff0000, v142
	v_fmac_f32_e32 v104, v105, v111
	v_mul_f32_e32 v105, 0xbfb8aa3b, v106
	v_exp_f32_e32 v105, v105
	v_mul_f32_e32 v107, 0xbfb8aa3b, v107
	v_pk_mul_f32 v[100:101], v[100:101], v[168:169] op_sel_hi:[1,0]
	v_exp_f32_e32 v107, v107
	v_mul_f32_e32 v100, 0xbfb8aa3b, v100
	v_exp_f32_e32 v100, v100
	v_mul_f32_e32 v101, 0xbfb8aa3b, v101
	v_exp_f32_e32 v101, v101
	v_add_f32_e32 v105, 1.0, v105
	v_rcp_f32_e32 v105, v105
	v_add_f32_e32 v107, 1.0, v107
	v_rcp_f32_e32 v107, v107
	v_add_f32_e32 v100, 1.0, v100
	v_rcp_f32_e32 v100, v100
	v_add_f32_e32 v101, 1.0, v101
	v_lshlrev_b32_e32 v106, 16, v139
	v_lshlrev_b32_e32 v111, 16, v143
	v_rcp_f32_e32 v101, v101
	v_fmac_f32_e32 v106, v105, v111
	v_and_b32_e32 v105, 0xffff0000, v139
	v_and_b32_e32 v111, 0xffff0000, v143
	v_fmac_f32_e32 v105, v107, v111
	s_waitcnt vmcnt(7)
	v_lshlrev_b32_e32 v107, 16, v128
	v_lshlrev_b32_e32 v111, 16, v132
	v_pk_mul_f32 v[102:103], v[102:103], v[168:169] op_sel_hi:[1,0]
	v_fmac_f32_e32 v107, v100, v111
	v_and_b32_e32 v100, 0xffff0000, v128
	v_and_b32_e32 v111, 0xffff0000, v132
	v_fmac_f32_e32 v100, v101, v111
	v_mul_f32_e32 v101, 0xbfb8aa3b, v102
	v_pk_mul_f32 v[96:97], v[96:97], v[168:169] op_sel_hi:[1,0]
	v_exp_f32_e32 v101, v101
	v_mul_f32_e32 v103, 0xbfb8aa3b, v103
	v_exp_f32_e32 v103, v103
	v_mul_f32_e32 v96, 0xbfb8aa3b, v96
	v_exp_f32_e32 v96, v96
	v_mul_f32_e32 v97, 0xbfb8aa3b, v97
	v_exp_f32_e32 v97, v97
	v_add_f32_e32 v101, 1.0, v101
	v_rcp_f32_e32 v101, v101
	v_add_f32_e32 v103, 1.0, v103
	v_rcp_f32_e32 v103, v103
	v_add_f32_e32 v96, 1.0, v96
	v_rcp_f32_e32 v96, v96
	v_add_f32_e32 v97, 1.0, v97
	v_lshlrev_b32_e32 v102, 16, v129
	v_lshlrev_b32_e32 v111, 16, v133
	v_rcp_f32_e32 v97, v97
	v_fmac_f32_e32 v102, v101, v111
	v_and_b32_e32 v101, 0xffff0000, v129
	v_and_b32_e32 v111, 0xffff0000, v133
	v_fmac_f32_e32 v101, v103, v111
	v_lshlrev_b32_e32 v103, 16, v130
	v_lshlrev_b32_e32 v111, 16, v134
	v_pk_mul_f32 v[98:99], v[98:99], v[168:169] op_sel_hi:[1,0]
	v_fmac_f32_e32 v103, v96, v111
	v_and_b32_e32 v111, 0xffff0000, v130
	v_and_b32_e32 v96, 0xffff0000, v134
	v_fmac_f32_e32 v111, v97, v96
	v_mul_f32_e32 v96, 0xbfb8aa3b, v98
	v_exp_f32_e32 v96, v96
	v_mul_f32_e32 v97, 0xbfb8aa3b, v99
	v_exp_f32_e32 v97, v97
	v_lshlrev_b32_e32 v128, 16, v131
	v_add_f32_e32 v96, 1.0, v96
	v_rcp_f32_e32 v96, v96
	v_add_f32_e32 v97, 1.0, v97
	v_rcp_f32_e32 v97, v97
	v_lshlrev_b32_e32 v98, 16, v135
	v_fmac_f32_e32 v128, v96, v98
	v_and_b32_e32 v129, 0xffff0000, v131
	v_and_b32_e32 v96, 0xffff0000, v135
	v_fmac_f32_e32 v129, v97, v96
	v_cvt_pk_bf16_f32 v96, v212, v136
	v_cvt_pk_bf16_f32 v97, v110, v108
	v_cvt_pk_bf16_f32 v98, v109, v104
	v_cvt_pk_bf16_f32 v99, v106, v105
	global_store_dwordx4 v[210:211], v[96:99], off sc1
	v_lshlrev_b32_e32 v104, 16, v96
	s_nop 0
	v_and_b32_e32 v96, 0xffff0000, v96
	v_mul_f32_e32 v96, v96, v96
	v_fmac_f32_e32 v96, v104, v104
	v_lshlrev_b32_e32 v104, 16, v97
	v_and_b32_e32 v97, 0xffff0000, v97
	v_mul_f32_e32 v97, v97, v97
	v_fmac_f32_e32 v97, v104, v104
	v_add_f32_e32 v96, v96, v97
	v_lshlrev_b32_e32 v97, 16, v98
	v_and_b32_e32 v98, 0xffff0000, v98
	v_mul_f32_e32 v98, v98, v98
	v_fmac_f32_e32 v98, v97, v97
	v_add_f32_e32 v96, v96, v98
	v_and_b32_e32 v98, 0xffff0000, v99
	v_lshlrev_b32_e32 v97, 16, v99
	v_mul_f32_e32 v98, v98, v98
	v_fmac_f32_e32 v98, v97, v97
	v_add_f32_e32 v96, v96, v98
	v_cvt_pk_bf16_f32 v98, v107, v100
	v_cvt_pk_bf16_f32 v99, v102, v101
	v_cvt_pk_bf16_f32 v100, v103, v111
	v_cvt_pk_bf16_f32 v101, v128, v129
	global_store_dwordx4 v[206:207], v[98:101], off sc1
	v_and_b32_e32 v102, 0xffff0000, v98
	v_lshlrev_b32_e32 v97, 16, v98
	v_mul_f32_e32 v102, v102, v102
	v_fmac_f32_e32 v102, v97, v97
	v_add_f32_e32 v96, v96, v102
	v_and_b32_e32 v102, 0xffff0000, v99
	v_lshlrev_b32_e32 v97, 16, v99
	v_mul_f32_e32 v102, v102, v102
	v_fmac_f32_e32 v102, v97, v97
	v_add_f32_e32 v96, v96, v102
	v_and_b32_e32 v102, 0xffff0000, v100
	v_lshlrev_b32_e32 v97, 16, v100
	v_mul_f32_e32 v102, v102, v102
	v_fmac_f32_e32 v102, v97, v97
	v_add_f32_e32 v96, v96, v102
	v_and_b32_e32 v102, 0xffff0000, v101
	v_lshlrev_b32_e32 v97, 16, v101
	v_mul_f32_e32 v102, v102, v102
	v_fmac_f32_e32 v102, v97, v97
	v_add_f32_e32 v96, v96, v102
	ds_bpermute_b32 v97, v191, v96
	s_waitcnt lgkmcnt(0)
	v_add_f32_e32 v96, v96, v97
	ds_bpermute_b32 v97, v214, v96
	s_and_saveexec_b64 s[12:13], vcc
	s_cbranch_execz .LBB0_242
	s_waitcnt lgkmcnt(0)
	v_add_f32_e32 v96, v96, v97
	v_mul_f32_e32 v96, 0x49800000, v96
	v_trunc_f32_e32 v96, v96
	v_mul_f32_e32 v97, 0x2f800000, v96
	v_floor_f32_e32 v97, v97
	v_fmac_f32_e32 v96, 0xcf800000, v97
	v_cvt_u32_f32_e32 v96, v96
	v_cvt_u32_f32_e32 v97, v97
	global_atomic_add_x2 v[192:193], v[96:97], off offset:128
; #define EP_LOAD(q) do { _Pragma("unroll") for (int bj = 0; bj < 2; ++bj) { const unsigned o = ER_OFF(q, bj); t[(q) & 1][bj] = *(const u32x4*)(base + o); pw[(q) & 1][bj] = *(const u32x4*)(pp + o); } } while (0)
;     __device__ __forceinline__ void operator()(f32x4 (&acc)[2][2][4][2], const Unit& u, int wr, int wc, int fr, int fq) const {
;     ...
;         bf16_t* hb = pp;
;         EP_LOAD(0); EP_LOAD(1); EP_ADD(0); EP_ADD(1);
; #pragma unroll
;         for (int q = 0; q < 8; q += 2) { if (q < 6) { EP_LOAD(q + 2); EP_LOAD(q + 3); } ER_STORE(q); ER_STORE(q + 1); if (q < 6) { EP_ADD(q + 2); EP_ADD(q + 3); } }
.LBB0_242:
	s_or_b64 exec, exec, s[12:13]
	v_ffbh_u32_e32 v96, v203
	v_min_u32_e32 v98, 32, v96
	s_waitcnt lgkmcnt(0)
	v_lshlrev_b64 v[96:97], v98, v[202:203]
	v_min_u32_e32 v96, 1, v96
	v_or_b32_e32 v96, v97, v96
	v_cvt_f32_u32_e32 v96, v96
	v_sub_u32_e32 v97, 32, v98
	v_lshlrev_b32_e32 v136, 16, v152
	v_and_b32_e32 v137, 0xffff0000, v152
	v_ldexp_f32 v96, v96, v97
	v_fmamk_f32 v96, v96, 0x30800000, v223
	v_rsq_f32_e32 v96, v96
	v_lshlrev_b32_e32 v138, 16, v153
	v_and_b32_e32 v139, 0xffff0000, v153
	v_lshlrev_b32_e32 v140, 16, v154
	v_pk_mul_f32 v[92:93], v[92:93], v[96:97] op_sel_hi:[1,0]
	v_pk_mul_f32 v[94:95], v[94:95], v[96:97] op_sel_hi:[1,0]
	v_mul_f32_e32 v92, 0xbfb8aa3b, v92
	v_exp_f32_e32 v92, v92
	v_mul_f32_e32 v93, 0xbfb8aa3b, v93
	v_exp_f32_e32 v93, v93
	v_pk_mul_f32 v[90:91], v[90:91], v[96:97] op_sel_hi:[1,0]
	v_add_f32_e32 v92, 1.0, v92
	v_rcp_f32_e32 v92, v92
	v_add_f32_e32 v93, 1.0, v93
	v_rcp_f32_e32 v93, v93
	v_pk_mul_f32 v[88:89], v[88:89], v[96:97] op_sel_hi:[1,0]
	s_waitcnt vmcnt(8)
	v_lshlrev_b32_e32 v97, 16, v156
	v_fmac_f32_e32 v136, v92, v97
	v_and_b32_e32 v92, 0xffff0000, v156
	v_fmac_f32_e32 v137, v93, v92
	v_mul_f32_e32 v93, 0xbfb8aa3b, v94
	v_exp_f32_e32 v93, v93
	v_lshlrev_b32_e32 v92, 16, v157
	v_mul_f32_e32 v88, 0xbfb8aa3b, v88
	v_exp_f32_e32 v88, v88
	v_add_f32_e32 v93, 1.0, v93
	v_rcp_f32_e32 v93, v93
	v_mul_f32_e32 v89, 0xbfb8aa3b, v89
	v_exp_f32_e32 v89, v89
	v_add_f32_e32 v88, 1.0, v88
	v_fmac_f32_e32 v138, v93, v92
	v_mul_f32_e32 v93, 0xbfb8aa3b, v95
	v_exp_f32_e32 v93, v93
	v_rcp_f32_e32 v88, v88
	v_add_f32_e32 v89, 1.0, v89
	v_rcp_f32_e32 v89, v89
	v_add_f32_e32 v93, 1.0, v93
	v_rcp_f32_e32 v93, v93
	v_and_b32_e32 v92, 0xffff0000, v157
	v_and_b32_e32 v141, 0xffff0000, v154
	v_lshlrev_b32_e32 v142, 16, v155
	v_fmac_f32_e32 v139, v93, v92
	v_lshlrev_b32_e32 v92, 16, v158
	v_fmac_f32_e32 v140, v88, v92
	v_and_b32_e32 v88, 0xffff0000, v158
	v_fmac_f32_e32 v141, v89, v88
	v_mul_f32_e32 v89, 0xbfb8aa3b, v90
	v_exp_f32_e32 v89, v89
	v_lshlrev_b32_e32 v88, 16, v159
	v_pk_mul_f32 v[84:85], v[84:85], v[96:97] op_sel_hi:[1,0]
	v_and_b32_e32 v143, 0xffff0000, v155
	v_add_f32_e32 v89, 1.0, v89
	v_rcp_f32_e32 v89, v89
	v_mul_f32_e32 v84, 0xbfb8aa3b, v84
	v_exp_f32_e32 v84, v84
	v_mul_f32_e32 v85, 0xbfb8aa3b, v85
	v_fmac_f32_e32 v142, v89, v88
	v_mul_f32_e32 v89, 0xbfb8aa3b, v91
	v_exp_f32_e32 v89, v89
	v_exp_f32_e32 v85, v85
	v_add_f32_e32 v84, 1.0, v84
	v_rcp_f32_e32 v84, v84
	v_add_f32_e32 v89, 1.0, v89
	v_rcp_f32_e32 v89, v89
	v_add_f32_e32 v85, 1.0, v85
	v_rcp_f32_e32 v85, v85
	v_and_b32_e32 v88, 0xffff0000, v159
	v_fmac_f32_e32 v143, v89, v88
	v_lshlrev_b32_e32 v152, 16, v144
	s_waitcnt vmcnt(7)
	v_lshlrev_b32_e32 v88, 16, v148
	v_pk_mul_f32 v[86:87], v[86:87], v[96:97] op_sel_hi:[1,0]
	v_fmac_f32_e32 v152, v84, v88
	v_and_b32_e32 v144, 0xffff0000, v144
	v_and_b32_e32 v84, 0xffff0000, v148
	v_fmac_f32_e32 v144, v85, v84
	v_mul_f32_e32 v85, 0xbfb8aa3b, v86
	v_exp_f32_e32 v85, v85
	v_lshlrev_b32_e32 v148, 16, v145
	v_lshlrev_b32_e32 v84, 16, v149
	v_pk_mul_f32 v[80:81], v[80:81], v[96:97] op_sel_hi:[1,0]
	v_add_f32_e32 v85, 1.0, v85
	v_rcp_f32_e32 v85, v85
	v_mul_f32_e32 v80, 0xbfb8aa3b, v80
	v_exp_f32_e32 v80, v80
	v_mul_f32_e32 v81, 0xbfb8aa3b, v81
	v_fmac_f32_e32 v148, v85, v84
	v_mul_f32_e32 v85, 0xbfb8aa3b, v87
	v_exp_f32_e32 v85, v85
	v_exp_f32_e32 v81, v81
	v_add_f32_e32 v80, 1.0, v80
	v_rcp_f32_e32 v80, v80
	v_add_f32_e32 v85, 1.0, v85
	v_rcp_f32_e32 v85, v85
	v_add_f32_e32 v81, 1.0, v81
	v_rcp_f32_e32 v81, v81
	v_and_b32_e32 v145, 0xffff0000, v145
	v_and_b32_e32 v84, 0xffff0000, v149
	v_fmac_f32_e32 v145, v85, v84
	v_lshlrev_b32_e32 v149, 16, v146
	v_lshlrev_b32_e32 v84, 16, v150
	v_pk_mul_f32 v[82:83], v[82:83], v[96:97] op_sel_hi:[1,0]
	v_fmac_f32_e32 v149, v80, v84
	v_and_b32_e32 v146, 0xffff0000, v146
	v_and_b32_e32 v80, 0xffff0000, v150
	v_fmac_f32_e32 v146, v81, v80
	v_mul_f32_e32 v81, 0xbfb8aa3b, v82
	v_exp_f32_e32 v81, v81
	v_lshlrev_b32_e32 v150, 16, v147
	v_lshlrev_b32_e32 v80, 16, v151
	v_and_b32_e32 v147, 0xffff0000, v147
	v_add_f32_e32 v81, 1.0, v81
	v_rcp_f32_e32 v81, v81
	v_add_u32_e32 v168, 0x20000, v190
	v_fmac_f32_e32 v150, v81, v80
	v_mul_f32_e32 v81, 0xbfb8aa3b, v83
	v_exp_f32_e32 v81, v81
	v_and_b32_e32 v80, 0xffff0000, v151
	v_add_f32_e32 v81, 1.0, v81
	v_rcp_f32_e32 v81, v81
	s_nop 0
	v_fmac_f32_e32 v147, v81, v80
	v_lshlrev_b64 v[80:81], 1, v[168:169]
	v_add_u32_e32 v168, 0x20080, v190
	v_lshl_add_u64 v[82:83], s[70:71], 0, v[80:81]
	v_lshl_add_u64 v[134:135], s[20:21], 0, v[80:81]
	v_lshlrev_b64 v[80:81], 1, v[168:169]
	v_lshl_add_u64 v[132:133], s[20:21], 0, v[80:81]
	v_add_u32_e32 v168, 0x24000, v190
	global_load_dwordx4 v[104:107], v[82:83], off
	global_load_dwordx4 v[100:103], v[132:133], off
	v_lshl_add_u64 v[82:83], s[70:71], 0, v[80:81]
	v_lshlrev_b64 v[80:81], 1, v[168:169]
	v_add_u32_e32 v168, 0x24080, v190
	v_lshl_add_u64 v[130:131], s[20:21], 0, v[80:81]
	v_lshlrev_b64 v[84:85], 1, v[168:169]
	global_load_dwordx4 v[96:99], v[82:83], off
	global_load_dwordx4 v[92:95], v[130:131], off
	v_lshl_add_u64 v[82:83], s[70:71], 0, v[80:81]
	v_lshl_add_u64 v[80:81], s[70:71], 0, v[84:85]
	v_lshl_add_u64 v[128:129], s[20:21], 0, v[84:85]
	global_load_dwordx4 v[108:111], v[134:135], off
	global_load_dwordx4 v[88:91], v[82:83], off
	global_load_dwordx4 v[84:87], v[128:129], off
	s_nop 0
	global_load_dwordx4 v[80:83], v[80:81], off
	v_cvt_pk_bf16_f32 v136, v136, v137
	v_cvt_pk_bf16_f32 v137, v138, v139
	v_cvt_pk_bf16_f32 v138, v140, v141
	v_cvt_pk_bf16_f32 v139, v142, v143
	global_store_dwordx4 v[208:209], v[136:139], off sc1
	v_lshlrev_b32_e32 v140, 16, v136
	s_nop 0
; #define EP_LOAD(q) do { _Pragma("unroll") for (int bj = 0; bj < 2; ++bj) { const unsigned o = ER_OFF(q, bj); t[(q) & 1][bj] = *(const u32x4*)(base + o); pw[(q) & 1][bj] = *(const u32x4*)(pp + o); } } while (0)
;     __device__ __forceinline__ void operator()(f32x4 (&acc)[2][2][4][2], const Unit& u, int wr, int wc, int fr, int fq) const {
;     ...
;         bf16_t* hb = pp;
;         EP_LOAD(0); EP_LOAD(1); EP_ADD(0); EP_ADD(1);
; #pragma unroll
;         for (int q = 0; q < 8; q += 2) { if (q < 6) { EP_LOAD(q + 2); EP_LOAD(q + 3); } ER_STORE(q); ER_STORE(q + 1); if (q < 6) { EP_ADD(q + 2); EP_ADD(q + 3); } }
	v_and_b32_e32 v136, 0xffff0000, v136
	v_mul_f32_e32 v136, v136, v136
	v_fmac_f32_e32 v136, v140, v140
	v_lshlrev_b32_e32 v140, 16, v137
	v_and_b32_e32 v137, 0xffff0000, v137
	v_mul_f32_e32 v137, v137, v137
	v_fmac_f32_e32 v137, v140, v140
	v_add_f32_e32 v136, v136, v137
	v_lshlrev_b32_e32 v137, 16, v138
	v_and_b32_e32 v138, 0xffff0000, v138
	v_mul_f32_e32 v138, v138, v138
	v_fmac_f32_e32 v138, v137, v137
	v_add_f32_e32 v136, v136, v138
	v_and_b32_e32 v138, 0xffff0000, v139
	v_lshlrev_b32_e32 v137, 16, v139
	v_mul_f32_e32 v138, v138, v138
	v_fmac_f32_e32 v138, v137, v137
	v_add_f32_e32 v140, v136, v138
	v_cvt_pk_bf16_f32 v136, v152, v144
	v_cvt_pk_bf16_f32 v137, v148, v145
	v_cvt_pk_bf16_f32 v138, v149, v146
	v_cvt_pk_bf16_f32 v139, v150, v147
	global_store_dwordx4 v[204:205], v[136:139], off sc1
	v_lshlrev_b32_e32 v141, 16, v136
	s_nop 0
	v_and_b32_e32 v136, 0xffff0000, v136
	v_mul_f32_e32 v136, v136, v136
	v_fmac_f32_e32 v136, v141, v141
	v_add_f32_e32 v136, v140, v136
	v_lshlrev_b32_e32 v140, 16, v137
	v_and_b32_e32 v137, 0xffff0000, v137
	v_mul_f32_e32 v137, v137, v137
	v_fmac_f32_e32 v137, v140, v140
	v_add_f32_e32 v136, v136, v137
	v_lshlrev_b32_e32 v137, 16, v138
	v_and_b32_e32 v138, 0xffff0000, v138
	v_mul_f32_e32 v138, v138, v138
	v_fmac_f32_e32 v138, v137, v137
	v_add_f32_e32 v136, v136, v138
	v_and_b32_e32 v138, 0xffff0000, v139
	v_lshlrev_b32_e32 v137, 16, v139
	v_mul_f32_e32 v138, v138, v138
	v_fmac_f32_e32 v138, v137, v137
	v_add_f32_e32 v136, v136, v138
	ds_bpermute_b32 v137, v191, v136
	s_waitcnt lgkmcnt(0)
	v_add_f32_e32 v136, v136, v137
	ds_bpermute_b32 v137, v214, v136
	s_and_saveexec_b64 s[12:13], vcc
	s_cbranch_execz .LBB0_244
	s_waitcnt lgkmcnt(0)
	v_add_f32_e32 v136, v136, v137
	v_mul_f32_e32 v136, 0x49800000, v136
	v_trunc_f32_e32 v136, v136
	v_mul_f32_e32 v137, 0x2f800000, v136
	v_floor_f32_e32 v137, v137
	v_fmac_f32_e32 v136, 0xcf800000, v137
	v_cvt_u32_f32_e32 v136, v136
	v_cvt_u32_f32_e32 v137, v137
	global_atomic_add_x2 v[192:193], v[136:137], off offset:256
.LBB0_244:
	s_or_b64 exec, exec, s[12:13]
	v_ffbh_u32_e32 v136, v197
	v_min_u32_e32 v138, 32, v136
	s_waitcnt lgkmcnt(0)
	v_lshlrev_b64 v[136:137], v138, v[196:197]
	v_min_u32_e32 v136, 1, v136
	v_or_b32_e32 v136, v137, v136
	v_cvt_f32_u32_e32 v136, v136
	v_sub_u32_e32 v137, 32, v138
	v_lshlrev_b32_e32 v138, 16, v124
	v_and_b32_e32 v124, 0xffff0000, v124
	v_ldexp_f32 v136, v136, v137
	v_fmamk_f32 v136, v136, 0x30800000, v223
	v_rsq_f32_e32 v136, v136
	s_waitcnt vmcnt(16)
	v_lshlrev_b32_e32 v137, 16, v120
	v_and_b32_e32 v120, 0xffff0000, v120
	v_pk_mul_f32 v[76:77], v[76:77], v[136:137] op_sel_hi:[1,0]
	s_nop 0
	v_mul_f32_e32 v76, 0xbfb8aa3b, v76
	v_mul_f32_e32 v77, 0xbfb8aa3b, v77
	v_exp_f32_e32 v139, v76
	v_exp_f32_e32 v140, v77
	v_pk_mul_f32 v[76:77], v[78:79], v[136:137] op_sel_hi:[1,0]
	v_pk_mul_f32 v[72:73], v[72:73], v[136:137] op_sel_hi:[1,0]
	v_mul_f32_e32 v76, 0xbfb8aa3b, v76
	v_exp_f32_e32 v76, v76
	v_mul_f32_e32 v77, 0xbfb8aa3b, v77
	v_exp_f32_e32 v77, v77
	v_mul_f32_e32 v72, 0xbfb8aa3b, v72
	v_exp_f32_e32 v72, v72
	v_mul_f32_e32 v73, 0xbfb8aa3b, v73
	v_add_f32_e32 v78, 1.0, v139
	v_add_f32_e32 v79, 1.0, v140
	v_exp_f32_e32 v73, v73
	v_rcp_f32_e32 v78, v78
	v_rcp_f32_e32 v79, v79
	v_add_f32_e32 v76, 1.0, v76
	v_rcp_f32_e32 v76, v76
	v_add_f32_e32 v77, 1.0, v77
	v_rcp_f32_e32 v77, v77
	v_add_f32_e32 v72, 1.0, v72
	v_rcp_f32_e32 v72, v72
	v_add_f32_e32 v73, 1.0, v73
	v_pk_mul_f32 v[74:75], v[74:75], v[136:137] op_sel_hi:[1,0]
	v_fmac_f32_e32 v137, v78, v138
	v_fmac_f32_e32 v120, v79, v124
	v_lshlrev_b32_e32 v78, 16, v121
	v_lshlrev_b32_e32 v79, 16, v125
	v_rcp_f32_e32 v73, v73
	v_fmac_f32_e32 v78, v76, v79
	v_and_b32_e32 v76, 0xffff0000, v121
	v_and_b32_e32 v79, 0xffff0000, v125
	v_fmac_f32_e32 v76, v77, v79
	v_lshlrev_b32_e32 v77, 16, v122
	v_lshlrev_b32_e32 v79, 16, v126
	v_fmac_f32_e32 v77, v72, v79
	v_and_b32_e32 v72, 0xffff0000, v122
	v_and_b32_e32 v79, 0xffff0000, v126
	v_fmac_f32_e32 v72, v73, v79
	v_mul_f32_e32 v73, 0xbfb8aa3b, v74
	v_exp_f32_e32 v73, v73
	v_mul_f32_e32 v75, 0xbfb8aa3b, v75
	v_pk_mul_f32 v[68:69], v[68:69], v[136:137] op_sel_hi:[1,0]
	v_exp_f32_e32 v75, v75
	v_mul_f32_e32 v68, 0xbfb8aa3b, v68
	v_exp_f32_e32 v68, v68
	v_mul_f32_e32 v69, 0xbfb8aa3b, v69
	v_exp_f32_e32 v69, v69
	v_add_f32_e32 v73, 1.0, v73
	v_rcp_f32_e32 v73, v73
	v_add_f32_e32 v75, 1.0, v75
	v_rcp_f32_e32 v75, v75
	v_add_f32_e32 v68, 1.0, v68
	v_rcp_f32_e32 v68, v68
	v_add_f32_e32 v69, 1.0, v69
	v_lshlrev_b32_e32 v74, 16, v123
	v_lshlrev_b32_e32 v79, 16, v127
	v_rcp_f32_e32 v69, v69
	v_fmac_f32_e32 v74, v73, v79
	v_and_b32_e32 v73, 0xffff0000, v123
	v_and_b32_e32 v79, 0xffff0000, v127
	v_fmac_f32_e32 v73, v75, v79
	s_waitcnt vmcnt(14)
; #define EP_LOAD(q) do { _Pragma("unroll") for (int bj = 0; bj < 2; ++bj) { const unsigned o = ER_OFF(q, bj); t[(q) & 1][bj] = *(const u32x4*)(base + o); pw[(q) & 1][bj] = *(const u32x4*)(pp + o); } } while (0)
;     __device__ __forceinline__ void operator()(f32x4 (&acc)[2][2][4][2], const Unit& u, int wr, int wc, int fr, int fq) const {
;     ...
;         bf16_t* hb = pp;
;         EP_LOAD(0); EP_LOAD(1); EP_ADD(0); EP_ADD(1);
; #pragma unroll
;         for (int q = 0; q < 8; q += 2) { if (q < 6) { EP_LOAD(q + 2); EP_LOAD(q + 3); } ER_STORE(q); ER_STORE(q + 1); if (q < 6) { EP_ADD(q + 2); EP_ADD(q + 3); } }
	v_lshlrev_b32_e32 v75, 16, v112
	v_lshlrev_b32_e32 v79, 16, v116
	v_pk_mul_f32 v[70:71], v[70:71], v[136:137] op_sel_hi:[1,0]
	v_fmac_f32_e32 v75, v68, v79
	v_and_b32_e32 v68, 0xffff0000, v112
	v_and_b32_e32 v79, 0xffff0000, v116
	v_fmac_f32_e32 v68, v69, v79
	v_mul_f32_e32 v69, 0xbfb8aa3b, v70
	v_pk_mul_f32 v[64:65], v[64:65], v[136:137] op_sel_hi:[1,0]
	v_exp_f32_e32 v69, v69
	v_mul_f32_e32 v71, 0xbfb8aa3b, v71
	v_exp_f32_e32 v71, v71
	v_mul_f32_e32 v64, 0xbfb8aa3b, v64
	v_exp_f32_e32 v64, v64
	v_mul_f32_e32 v65, 0xbfb8aa3b, v65
	v_exp_f32_e32 v65, v65
	v_add_f32_e32 v69, 1.0, v69
	v_rcp_f32_e32 v69, v69
	v_add_f32_e32 v71, 1.0, v71
	v_rcp_f32_e32 v71, v71
	v_add_f32_e32 v64, 1.0, v64
	v_rcp_f32_e32 v64, v64
	v_add_f32_e32 v65, 1.0, v65
	v_lshlrev_b32_e32 v70, 16, v113
	v_lshlrev_b32_e32 v79, 16, v117
	v_rcp_f32_e32 v65, v65
	v_fmac_f32_e32 v70, v69, v79
	v_and_b32_e32 v69, 0xffff0000, v113
	v_and_b32_e32 v79, 0xffff0000, v117
	v_fmac_f32_e32 v69, v71, v79
	v_lshlrev_b32_e32 v71, 16, v114
	v_lshlrev_b32_e32 v79, 16, v118
	v_pk_mul_f32 v[66:67], v[66:67], v[136:137] op_sel_hi:[1,0]
	v_fmac_f32_e32 v71, v64, v79
	v_and_b32_e32 v79, 0xffff0000, v114
	v_and_b32_e32 v64, 0xffff0000, v118
	v_fmac_f32_e32 v79, v65, v64
	v_mul_f32_e32 v64, 0xbfb8aa3b, v66
	v_exp_f32_e32 v64, v64
	v_mul_f32_e32 v65, 0xbfb8aa3b, v67
	v_exp_f32_e32 v65, v65
	v_lshlrev_b32_e32 v112, 16, v115
	v_add_f32_e32 v64, 1.0, v64
	v_rcp_f32_e32 v64, v64
	v_add_f32_e32 v65, 1.0, v65
	v_rcp_f32_e32 v65, v65
	v_lshlrev_b32_e32 v66, 16, v119
	v_fmac_f32_e32 v112, v64, v66
	v_and_b32_e32 v113, 0xffff0000, v115
	v_and_b32_e32 v64, 0xffff0000, v119
	v_fmac_f32_e32 v113, v65, v64
	v_cvt_pk_bf16_f32 v64, v137, v120
	v_cvt_pk_bf16_f32 v65, v78, v76
	v_cvt_pk_bf16_f32 v66, v77, v72
	v_cvt_pk_bf16_f32 v67, v74, v73
	global_store_dwordx4 v[200:201], v[64:67], off sc1
	v_lshlrev_b32_e32 v72, 16, v64
	s_nop 0
	v_and_b32_e32 v64, 0xffff0000, v64
	v_mul_f32_e32 v64, v64, v64
	v_fmac_f32_e32 v64, v72, v72
	v_lshlrev_b32_e32 v72, 16, v65
	v_and_b32_e32 v65, 0xffff0000, v65
	v_mul_f32_e32 v65, v65, v65
	v_fmac_f32_e32 v65, v72, v72
	v_add_f32_e32 v64, v64, v65
	v_lshlrev_b32_e32 v65, 16, v66
	v_and_b32_e32 v66, 0xffff0000, v66
	v_mul_f32_e32 v66, v66, v66
	v_fmac_f32_e32 v66, v65, v65
	v_add_f32_e32 v64, v64, v66
	v_and_b32_e32 v66, 0xffff0000, v67
	v_lshlrev_b32_e32 v65, 16, v67
	v_mul_f32_e32 v66, v66, v66
	v_fmac_f32_e32 v66, v65, v65
	v_add_f32_e32 v64, v64, v66
	v_cvt_pk_bf16_f32 v66, v75, v68
	v_cvt_pk_bf16_f32 v67, v70, v69
	v_cvt_pk_bf16_f32 v68, v71, v79
	v_cvt_pk_bf16_f32 v69, v112, v113
	global_store_dwordx4 v[198:199], v[66:69], off sc1
	v_and_b32_e32 v70, 0xffff0000, v66
	v_lshlrev_b32_e32 v65, 16, v66
	v_mul_f32_e32 v70, v70, v70
	v_fmac_f32_e32 v70, v65, v65
	v_add_f32_e32 v64, v64, v70
	v_and_b32_e32 v70, 0xffff0000, v67
	v_lshlrev_b32_e32 v65, 16, v67
	v_mul_f32_e32 v70, v70, v70
	v_fmac_f32_e32 v70, v65, v65
	v_add_f32_e32 v64, v64, v70
	v_and_b32_e32 v70, 0xffff0000, v68
	v_lshlrev_b32_e32 v65, 16, v68
	v_mul_f32_e32 v70, v70, v70
	v_fmac_f32_e32 v70, v65, v65
	v_add_f32_e32 v64, v64, v70
	v_and_b32_e32 v70, 0xffff0000, v69
	v_lshlrev_b32_e32 v65, 16, v69
	v_mul_f32_e32 v70, v70, v70
	v_fmac_f32_e32 v70, v65, v65
	v_add_f32_e32 v64, v64, v70
	ds_bpermute_b32 v65, v191, v64
	s_waitcnt lgkmcnt(0)
	v_add_f32_e32 v64, v64, v65
	ds_bpermute_b32 v65, v214, v64
	s_and_saveexec_b64 s[12:13], vcc
	s_cbranch_execz .LBB0_246
	s_waitcnt lgkmcnt(0)
	v_add_f32_e32 v64, v64, v65
	v_mul_f32_e32 v64, 0x49800000, v64
	v_trunc_f32_e32 v64, v64
	v_mul_f32_e32 v65, 0x2f800000, v64
	v_floor_f32_e32 v65, v65
	v_fmac_f32_e32 v64, 0xcf800000, v65
	v_cvt_u32_f32_e32 v64, v64
	v_cvt_u32_f32_e32 v65, v65
	global_atomic_add_x2 v[192:193], v[64:65], off offset:384
.LBB0_246:
	s_or_b64 exec, exec, s[12:13]
	v_ffbh_u32_e32 v64, v195
	v_min_u32_e32 v66, 32, v64
	s_waitcnt lgkmcnt(0)
	v_lshlrev_b64 v[64:65], v66, v[194:195]
	v_min_u32_e32 v64, 1, v64
	v_or_b32_e32 v64, v65, v64
	v_cvt_f32_u32_e32 v64, v64
	v_sub_u32_e32 v65, 32, v66
	s_waitcnt vmcnt(11)
	v_lshlrev_b32_e32 v112, 16, v104
	v_and_b32_e32 v104, 0xffff0000, v104
	v_ldexp_f32 v64, v64, v65
	v_fmamk_f32 v64, v64, 0x30800000, v223
	v_rsq_f32_e32 v64, v64
	s_waitcnt vmcnt(9)
	v_and_b32_e32 v113, 0xffff0000, v96
	v_lshlrev_b32_e32 v114, 16, v97
	v_and_b32_e32 v115, 0xffff0000, v97
	v_pk_mul_f32 v[60:61], v[60:61], v[64:65] op_sel_hi:[1,0]
	v_pk_mul_f32 v[62:63], v[62:63], v[64:65] op_sel_hi:[1,0]
	v_mul_f32_e32 v60, 0xbfb8aa3b, v60
	v_exp_f32_e32 v60, v60
	v_mul_f32_e32 v61, 0xbfb8aa3b, v61
	v_exp_f32_e32 v61, v61
	v_pk_mul_f32 v[58:59], v[58:59], v[64:65] op_sel_hi:[1,0]
	v_add_f32_e32 v60, 1.0, v60
	v_rcp_f32_e32 v60, v60
	v_add_f32_e32 v61, 1.0, v61
	v_rcp_f32_e32 v61, v61
	v_pk_mul_f32 v[56:57], v[56:57], v[64:65] op_sel_hi:[1,0]
	s_waitcnt vmcnt(7)
; #define EP_LOAD(q) do { _Pragma("unroll") for (int bj = 0; bj < 2; ++bj) { const unsigned o = ER_OFF(q, bj); t[(q) & 1][bj] = *(const u32x4*)(base + o); pw[(q) & 1][bj] = *(const u32x4*)(pp + o); } } while (0)
;     __device__ __forceinline__ void operator()(f32x4 (&acc)[2][2][4][2], const Unit& u, int wr, int wc, int fr, int fq) const {
;     ...
;         bf16_t* hb = pp;
;         EP_LOAD(0); EP_LOAD(1); EP_ADD(0); EP_ADD(1);
; #pragma unroll
;         for (int q = 0; q < 8; q += 2) { if (q < 6) { EP_LOAD(q + 2); EP_LOAD(q + 3); } ER_STORE(q); ER_STORE(q + 1); if (q < 6) { EP_ADD(q + 2); EP_ADD(q + 3); } }
	v_lshlrev_b32_e32 v65, 16, v108
	v_fmac_f32_e32 v112, v60, v65
	v_and_b32_e32 v60, 0xffff0000, v108
	v_fmac_f32_e32 v104, v61, v60
	v_mul_f32_e32 v61, 0xbfb8aa3b, v62
	v_exp_f32_e32 v61, v61
	v_lshlrev_b32_e32 v108, 16, v105
	v_lshlrev_b32_e32 v60, 16, v109
	v_mul_f32_e32 v56, 0xbfb8aa3b, v56
	v_add_f32_e32 v61, 1.0, v61
	v_rcp_f32_e32 v61, v61
	v_exp_f32_e32 v56, v56
	v_mul_f32_e32 v57, 0xbfb8aa3b, v57
	v_exp_f32_e32 v57, v57
	v_fmac_f32_e32 v108, v61, v60
	v_mul_f32_e32 v61, 0xbfb8aa3b, v63
	v_exp_f32_e32 v61, v61
	v_add_f32_e32 v56, 1.0, v56
	v_rcp_f32_e32 v56, v56
	v_add_f32_e32 v57, 1.0, v57
	v_add_f32_e32 v61, 1.0, v61
	v_rcp_f32_e32 v61, v61
	v_rcp_f32_e32 v57, v57
	v_and_b32_e32 v105, 0xffff0000, v105
	v_and_b32_e32 v60, 0xffff0000, v109
	v_fmac_f32_e32 v105, v61, v60
	v_lshlrev_b32_e32 v109, 16, v106
	v_lshlrev_b32_e32 v60, 16, v110
	v_fmac_f32_e32 v109, v56, v60
	v_and_b32_e32 v106, 0xffff0000, v106
	v_and_b32_e32 v56, 0xffff0000, v110
	v_fmac_f32_e32 v106, v57, v56
	v_mul_f32_e32 v57, 0xbfb8aa3b, v58
	v_exp_f32_e32 v57, v57
	v_lshlrev_b32_e32 v110, 16, v107
	v_lshlrev_b32_e32 v56, 16, v111
	v_pk_mul_f32 v[52:53], v[52:53], v[64:65] op_sel_hi:[1,0]
	v_add_f32_e32 v57, 1.0, v57
	v_rcp_f32_e32 v57, v57
	v_mul_f32_e32 v52, 0xbfb8aa3b, v52
	v_exp_f32_e32 v52, v52
	v_mul_f32_e32 v53, 0xbfb8aa3b, v53
	v_fmac_f32_e32 v110, v57, v56
	v_mul_f32_e32 v57, 0xbfb8aa3b, v59
	v_exp_f32_e32 v57, v57
	v_exp_f32_e32 v53, v53
	v_add_f32_e32 v52, 1.0, v52
	v_rcp_f32_e32 v52, v52
	v_add_f32_e32 v57, 1.0, v57
	v_rcp_f32_e32 v57, v57
	v_add_f32_e32 v53, 1.0, v53
	v_rcp_f32_e32 v53, v53
	v_and_b32_e32 v107, 0xffff0000, v107
	v_and_b32_e32 v56, 0xffff0000, v111
	v_fmac_f32_e32 v107, v57, v56
	v_lshlrev_b32_e32 v111, 16, v96
	v_lshlrev_b32_e32 v56, 16, v100
	v_pk_mul_f32 v[54:55], v[54:55], v[64:65] op_sel_hi:[1,0]
	v_fmac_f32_e32 v111, v52, v56
	v_and_b32_e32 v52, 0xffff0000, v100
	v_fmac_f32_e32 v113, v53, v52
	v_mul_f32_e32 v53, 0xbfb8aa3b, v54
	v_exp_f32_e32 v53, v53
	v_lshlrev_b32_e32 v52, 16, v101
	v_pk_mul_f32 v[48:49], v[48:49], v[64:65] op_sel_hi:[1,0]
	v_lshlrev_b32_e32 v116, 16, v98
	v_add_f32_e32 v53, 1.0, v53
	v_rcp_f32_e32 v53, v53
	v_mul_f32_e32 v48, 0xbfb8aa3b, v48
	v_exp_f32_e32 v48, v48
	v_mul_f32_e32 v49, 0xbfb8aa3b, v49
	v_fmac_f32_e32 v114, v53, v52
	v_mul_f32_e32 v53, 0xbfb8aa3b, v55
	v_exp_f32_e32 v53, v53
	v_exp_f32_e32 v49, v49
	v_add_f32_e32 v48, 1.0, v48
	v_rcp_f32_e32 v48, v48
	v_add_f32_e32 v53, 1.0, v53
	v_rcp_f32_e32 v53, v53
	v_add_f32_e32 v49, 1.0, v49
	v_rcp_f32_e32 v49, v49
	v_and_b32_e32 v52, 0xffff0000, v101
	v_fmac_f32_e32 v115, v53, v52
	v_lshlrev_b32_e32 v52, 16, v102
	v_pk_mul_f32 v[50:51], v[50:51], v[64:65] op_sel_hi:[1,0]
	v_fmac_f32_e32 v116, v48, v52
	v_and_b32_e32 v117, 0xffff0000, v98
	v_and_b32_e32 v48, 0xffff0000, v102
	v_fmac_f32_e32 v117, v49, v48
	v_mul_f32_e32 v49, 0xbfb8aa3b, v50
	v_exp_f32_e32 v49, v49
	v_lshlrev_b32_e32 v118, 16, v99
	v_lshlrev_b32_e32 v48, 16, v103
	v_and_b32_e32 v119, 0xffff0000, v99
	v_add_f32_e32 v49, 1.0, v49
	v_rcp_f32_e32 v49, v49
	v_add_u32_e32 v168, 0x28000, v190
	v_fmac_f32_e32 v118, v49, v48
	v_mul_f32_e32 v49, 0xbfb8aa3b, v51
	v_exp_f32_e32 v49, v49
	v_and_b32_e32 v48, 0xffff0000, v103
	v_add_f32_e32 v49, 1.0, v49
	v_rcp_f32_e32 v49, v49
	s_nop 0
	v_fmac_f32_e32 v119, v49, v48
	v_lshlrev_b64 v[48:49], 1, v[168:169]
	v_add_u32_e32 v168, 0x28080, v190
	v_lshl_add_u64 v[50:51], s[70:71], 0, v[48:49]
	v_lshl_add_u64 v[102:103], s[20:21], 0, v[48:49]
	v_lshlrev_b64 v[48:49], 1, v[168:169]
	v_lshl_add_u64 v[100:101], s[20:21], 0, v[48:49]
	v_add_u32_e32 v168, 0x2c000, v190
	global_load_dwordx4 v[72:75], v[50:51], off
	global_load_dwordx4 v[68:71], v[100:101], off
	v_lshl_add_u64 v[50:51], s[70:71], 0, v[48:49]
	v_lshlrev_b64 v[48:49], 1, v[168:169]
	v_add_u32_e32 v168, 0x2c080, v190
	v_lshl_add_u64 v[98:99], s[20:21], 0, v[48:49]
	v_lshlrev_b64 v[52:53], 1, v[168:169]
	global_load_dwordx4 v[64:67], v[50:51], off
	global_load_dwordx4 v[60:63], v[98:99], off
	v_lshl_add_u64 v[50:51], s[70:71], 0, v[48:49]
	v_lshl_add_u64 v[48:49], s[70:71], 0, v[52:53]
	v_lshl_add_u64 v[96:97], s[20:21], 0, v[52:53]
	global_load_dwordx4 v[76:79], v[102:103], off
	global_load_dwordx4 v[56:59], v[50:51], off
	global_load_dwordx4 v[52:55], v[96:97], off
	s_nop 0
	global_load_dwordx4 v[48:51], v[48:49], off
	v_cvt_pk_bf16_f32 v104, v112, v104
	v_cvt_pk_bf16_f32 v105, v108, v105
	v_cvt_pk_bf16_f32 v106, v109, v106
	v_cvt_pk_bf16_f32 v107, v110, v107
	global_store_dwordx4 v[134:135], v[104:107], off sc1
	v_lshlrev_b32_e32 v108, 16, v104
	s_nop 0
	v_and_b32_e32 v104, 0xffff0000, v104
	v_mul_f32_e32 v104, v104, v104
	v_fmac_f32_e32 v104, v108, v108
	v_lshlrev_b32_e32 v108, 16, v105
	v_and_b32_e32 v105, 0xffff0000, v105
	v_mul_f32_e32 v105, v105, v105
	v_fmac_f32_e32 v105, v108, v108
	v_add_f32_e32 v104, v104, v105
	v_lshlrev_b32_e32 v105, 16, v106
	v_and_b32_e32 v106, 0xffff0000, v106
	v_mul_f32_e32 v106, v106, v106
	v_fmac_f32_e32 v106, v105, v105
	v_add_f32_e32 v104, v104, v106
	v_and_b32_e32 v106, 0xffff0000, v107
	v_lshlrev_b32_e32 v105, 16, v107
	v_mul_f32_e32 v106, v106, v106
	v_fmac_f32_e32 v106, v105, v105
	v_add_f32_e32 v108, v104, v106
	v_cvt_pk_bf16_f32 v104, v111, v113
	v_cvt_pk_bf16_f32 v105, v114, v115
	v_cvt_pk_bf16_f32 v106, v116, v117
	v_cvt_pk_bf16_f32 v107, v118, v119
	global_store_dwordx4 v[132:133], v[104:107], off sc1
	v_lshlrev_b32_e32 v109, 16, v104
	s_nop 0
	v_and_b32_e32 v104, 0xffff0000, v104
	v_mul_f32_e32 v104, v104, v104
	v_fmac_f32_e32 v104, v109, v109
	v_add_f32_e32 v104, v108, v104
	v_lshlrev_b32_e32 v108, 16, v105
	v_and_b32_e32 v105, 0xffff0000, v105
	v_mul_f32_e32 v105, v105, v105
	v_fmac_f32_e32 v105, v108, v108
	v_add_f32_e32 v104, v104, v105
	v_lshlrev_b32_e32 v105, 16, v106
	v_and_b32_e32 v106, 0xffff0000, v106
	v_mul_f32_e32 v106, v106, v106
	v_fmac_f32_e32 v106, v105, v105
	v_add_f32_e32 v104, v104, v106
	v_and_b32_e32 v106, 0xffff0000, v107
	v_lshlrev_b32_e32 v105, 16, v107
	v_mul_f32_e32 v106, v106, v106
	v_fmac_f32_e32 v106, v105, v105
	v_add_f32_e32 v104, v104, v106
	ds_bpermute_b32 v105, v191, v104
	s_waitcnt lgkmcnt(0)
	v_add_f32_e32 v104, v104, v105
	ds_bpermute_b32 v105, v214, v104
	s_and_saveexec_b64 s[12:13], vcc
	s_cbranch_execz .LBB0_248
	s_waitcnt lgkmcnt(0)
	v_add_f32_e32 v104, v104, v105
	v_mul_f32_e32 v104, 0x49800000, v104
	v_trunc_f32_e32 v104, v104
	v_mul_f32_e32 v105, 0x2f800000, v104
	v_floor_f32_e32 v105, v105
	v_fmac_f32_e32 v104, 0xcf800000, v105
	v_cvt_u32_f32_e32 v104, v104
	v_cvt_u32_f32_e32 v105, v105
	global_atomic_add_x2 v[192:193], v[104:105], off offset:1024
; #define EP_LOAD(q) do { _Pragma("unroll") for (int bj = 0; bj < 2; ++bj) { const unsigned o = ER_OFF(q, bj); t[(q) & 1][bj] = *(const u32x4*)(base + o); pw[(q) & 1][bj] = *(const u32x4*)(pp + o); } } while (0)
;     __device__ __forceinline__ void operator()(f32x4 (&acc)[2][2][4][2], const Unit& u, int wr, int wc, int fr, int fq) const {
;     ...
;         bf16_t* hb = pp;
;         EP_LOAD(0); EP_LOAD(1); EP_ADD(0); EP_ADD(1);
; #pragma unroll
;         for (int q = 0; q < 8; q += 2) { if (q < 6) { EP_LOAD(q + 2); EP_LOAD(q + 3); } ER_STORE(q); ER_STORE(q + 1); if (q < 6) { EP_ADD(q + 2); EP_ADD(q + 3); } }
.LBB0_248:
	s_or_b64 exec, exec, s[12:13]
	v_ffbh_u32_e32 v104, v189
	v_min_u32_e32 v106, 32, v104
	s_waitcnt lgkmcnt(0)
	v_lshlrev_b64 v[104:105], v106, v[188:189]
	v_min_u32_e32 v104, 1, v104
	v_or_b32_e32 v104, v105, v104
	v_cvt_f32_u32_e32 v104, v104
	v_sub_u32_e32 v105, 32, v106
	v_lshlrev_b32_e32 v106, 16, v92
	v_and_b32_e32 v92, 0xffff0000, v92
	v_ldexp_f32 v104, v104, v105
	v_fmamk_f32 v104, v104, 0x30800000, v223
	v_rsq_f32_e32 v104, v104
	s_waitcnt vmcnt(16)
	v_lshlrev_b32_e32 v105, 16, v88
	v_and_b32_e32 v88, 0xffff0000, v88
	v_pk_mul_f32 v[44:45], v[44:45], v[104:105] op_sel_hi:[1,0]
	s_nop 0
	v_mul_f32_e32 v44, 0xbfb8aa3b, v44
	v_mul_f32_e32 v45, 0xbfb8aa3b, v45
	v_exp_f32_e32 v107, v44
	v_exp_f32_e32 v108, v45
	v_pk_mul_f32 v[44:45], v[46:47], v[104:105] op_sel_hi:[1,0]
	v_pk_mul_f32 v[40:41], v[40:41], v[104:105] op_sel_hi:[1,0]
	v_mul_f32_e32 v44, 0xbfb8aa3b, v44
	v_exp_f32_e32 v44, v44
	v_mul_f32_e32 v45, 0xbfb8aa3b, v45
	v_exp_f32_e32 v45, v45
	v_mul_f32_e32 v40, 0xbfb8aa3b, v40
	v_exp_f32_e32 v40, v40
	v_mul_f32_e32 v41, 0xbfb8aa3b, v41
	v_add_f32_e32 v46, 1.0, v107
	v_add_f32_e32 v47, 1.0, v108
	v_exp_f32_e32 v41, v41
	v_rcp_f32_e32 v46, v46
	v_rcp_f32_e32 v47, v47
	v_add_f32_e32 v44, 1.0, v44
	v_rcp_f32_e32 v44, v44
	v_add_f32_e32 v45, 1.0, v45
	v_rcp_f32_e32 v45, v45
	v_add_f32_e32 v40, 1.0, v40
	v_rcp_f32_e32 v40, v40
	v_add_f32_e32 v41, 1.0, v41
	v_pk_mul_f32 v[42:43], v[42:43], v[104:105] op_sel_hi:[1,0]
	v_fmac_f32_e32 v105, v46, v106
	v_fmac_f32_e32 v88, v47, v92
	v_lshlrev_b32_e32 v46, 16, v89
	v_lshlrev_b32_e32 v47, 16, v93
	v_rcp_f32_e32 v41, v41
	v_fmac_f32_e32 v46, v44, v47
	v_and_b32_e32 v44, 0xffff0000, v89
	v_and_b32_e32 v47, 0xffff0000, v93
	v_fmac_f32_e32 v44, v45, v47
	v_lshlrev_b32_e32 v45, 16, v90
	v_lshlrev_b32_e32 v47, 16, v94
	v_fmac_f32_e32 v45, v40, v47
	v_and_b32_e32 v40, 0xffff0000, v90
	v_and_b32_e32 v47, 0xffff0000, v94
	v_fmac_f32_e32 v40, v41, v47
	v_mul_f32_e32 v41, 0xbfb8aa3b, v42
	v_exp_f32_e32 v41, v41
	v_mul_f32_e32 v43, 0xbfb8aa3b, v43
	v_pk_mul_f32 v[36:37], v[36:37], v[104:105] op_sel_hi:[1,0]
	v_exp_f32_e32 v43, v43
	v_mul_f32_e32 v36, 0xbfb8aa3b, v36
	v_exp_f32_e32 v36, v36
	v_mul_f32_e32 v37, 0xbfb8aa3b, v37
	v_exp_f32_e32 v37, v37
	v_add_f32_e32 v41, 1.0, v41
	v_rcp_f32_e32 v41, v41
	v_add_f32_e32 v43, 1.0, v43
	v_rcp_f32_e32 v43, v43
	v_add_f32_e32 v36, 1.0, v36
	v_rcp_f32_e32 v36, v36
	v_add_f32_e32 v37, 1.0, v37
	v_lshlrev_b32_e32 v42, 16, v91
	v_lshlrev_b32_e32 v47, 16, v95
	v_rcp_f32_e32 v37, v37
	v_fmac_f32_e32 v42, v41, v47
	v_and_b32_e32 v41, 0xffff0000, v91
	v_and_b32_e32 v47, 0xffff0000, v95
	v_fmac_f32_e32 v41, v43, v47
	s_waitcnt vmcnt(14)
	v_lshlrev_b32_e32 v43, 16, v80
	v_lshlrev_b32_e32 v47, 16, v84
	v_pk_mul_f32 v[38:39], v[38:39], v[104:105] op_sel_hi:[1,0]
	v_fmac_f32_e32 v43, v36, v47
	v_and_b32_e32 v36, 0xffff0000, v80
	v_and_b32_e32 v47, 0xffff0000, v84
	v_fmac_f32_e32 v36, v37, v47
	v_mul_f32_e32 v37, 0xbfb8aa3b, v38
	v_pk_mul_f32 v[32:33], v[32:33], v[104:105] op_sel_hi:[1,0]
	v_exp_f32_e32 v37, v37
	v_mul_f32_e32 v39, 0xbfb8aa3b, v39
	v_exp_f32_e32 v39, v39
	v_mul_f32_e32 v32, 0xbfb8aa3b, v32
	v_exp_f32_e32 v32, v32
	v_mul_f32_e32 v33, 0xbfb8aa3b, v33
	v_exp_f32_e32 v33, v33
	v_add_f32_e32 v37, 1.0, v37
	v_rcp_f32_e32 v37, v37
	v_add_f32_e32 v39, 1.0, v39
	v_rcp_f32_e32 v39, v39
	v_add_f32_e32 v32, 1.0, v32
	v_rcp_f32_e32 v32, v32
	v_add_f32_e32 v33, 1.0, v33
	v_lshlrev_b32_e32 v38, 16, v81
	v_lshlrev_b32_e32 v47, 16, v85
	v_rcp_f32_e32 v33, v33
	v_fmac_f32_e32 v38, v37, v47
	v_and_b32_e32 v37, 0xffff0000, v81
	v_and_b32_e32 v47, 0xffff0000, v85
	v_fmac_f32_e32 v37, v39, v47
	v_lshlrev_b32_e32 v39, 16, v82
	v_lshlrev_b32_e32 v47, 16, v86
	v_pk_mul_f32 v[34:35], v[34:35], v[104:105] op_sel_hi:[1,0]
	v_fmac_f32_e32 v39, v32, v47
	v_and_b32_e32 v47, 0xffff0000, v82
	v_and_b32_e32 v32, 0xffff0000, v86
	v_fmac_f32_e32 v47, v33, v32
	v_mul_f32_e32 v32, 0xbfb8aa3b, v34
	v_exp_f32_e32 v32, v32
	v_mul_f32_e32 v33, 0xbfb8aa3b, v35
	v_exp_f32_e32 v33, v33
	v_lshlrev_b32_e32 v80, 16, v83
	v_add_f32_e32 v32, 1.0, v32
	v_rcp_f32_e32 v32, v32
	v_add_f32_e32 v33, 1.0, v33
	v_rcp_f32_e32 v33, v33
	v_lshlrev_b32_e32 v34, 16, v87
	v_fmac_f32_e32 v80, v32, v34
	v_and_b32_e32 v81, 0xffff0000, v83
	v_and_b32_e32 v32, 0xffff0000, v87
	v_fmac_f32_e32 v81, v33, v32
	v_cvt_pk_bf16_f32 v32, v105, v88
	v_cvt_pk_bf16_f32 v33, v46, v44
	v_cvt_pk_bf16_f32 v34, v45, v40
	v_cvt_pk_bf16_f32 v35, v42, v41
	global_store_dwordx4 v[130:131], v[32:35], off sc1
	v_lshlrev_b32_e32 v40, 16, v32
	s_nop 0
	v_and_b32_e32 v32, 0xffff0000, v32
	v_mul_f32_e32 v32, v32, v32
	v_fmac_f32_e32 v32, v40, v40
	v_lshlrev_b32_e32 v40, 16, v33
	v_and_b32_e32 v33, 0xffff0000, v33
	v_mul_f32_e32 v33, v33, v33
	v_fmac_f32_e32 v33, v40, v40
	v_add_f32_e32 v32, v32, v33
	v_lshlrev_b32_e32 v33, 16, v34
	v_and_b32_e32 v34, 0xffff0000, v34
	v_mul_f32_e32 v34, v34, v34
	v_fmac_f32_e32 v34, v33, v33
	v_add_f32_e32 v32, v32, v34
	v_and_b32_e32 v34, 0xffff0000, v35
	v_lshlrev_b32_e32 v33, 16, v35
	v_mul_f32_e32 v34, v34, v34
	v_fmac_f32_e32 v34, v33, v33
	v_add_f32_e32 v32, v32, v34
	v_cvt_pk_bf16_f32 v34, v43, v36
	v_cvt_pk_bf16_f32 v35, v38, v37
	v_cvt_pk_bf16_f32 v36, v39, v47
	v_cvt_pk_bf16_f32 v37, v80, v81
	global_store_dwordx4 v[128:129], v[34:37], off sc1
	v_and_b32_e32 v38, 0xffff0000, v34
	v_lshlrev_b32_e32 v33, 16, v34
	v_mul_f32_e32 v38, v38, v38
	v_fmac_f32_e32 v38, v33, v33
	v_add_f32_e32 v32, v32, v38
	v_and_b32_e32 v38, 0xffff0000, v35
	v_lshlrev_b32_e32 v33, 16, v35
	v_mul_f32_e32 v38, v38, v38
	v_fmac_f32_e32 v38, v33, v33
	v_add_f32_e32 v32, v32, v38
	v_and_b32_e32 v38, 0xffff0000, v36
	v_lshlrev_b32_e32 v33, 16, v36
	v_mul_f32_e32 v38, v38, v38
	v_fmac_f32_e32 v38, v33, v33
	v_add_f32_e32 v32, v32, v38
	v_and_b32_e32 v38, 0xffff0000, v37
	v_lshlrev_b32_e32 v33, 16, v37
	v_mul_f32_e32 v38, v38, v38
	v_fmac_f32_e32 v38, v33, v33
	v_add_f32_e32 v32, v32, v38
	ds_bpermute_b32 v33, v191, v32
	s_waitcnt lgkmcnt(0)
	v_add_f32_e32 v32, v32, v33
	ds_bpermute_b32 v33, v214, v32
	s_and_saveexec_b64 s[12:13], vcc
	s_cbranch_execz .LBB0_250
	s_waitcnt lgkmcnt(0)
	v_add_f32_e32 v32, v32, v33
	v_mul_f32_e32 v32, 0x49800000, v32
	v_trunc_f32_e32 v32, v32
	v_mul_f32_e32 v33, 0x2f800000, v32
	v_floor_f32_e32 v33, v33
	v_fmac_f32_e32 v32, 0xcf800000, v33
	v_cvt_u32_f32_e32 v32, v32
	v_cvt_u32_f32_e32 v33, v33
	global_atomic_add_x2 v[192:193], v[32:33], off offset:1152
; #define EP_LOAD(q) do { _Pragma("unroll") for (int bj = 0; bj < 2; ++bj) { const unsigned o = ER_OFF(q, bj); t[(q) & 1][bj] = *(const u32x4*)(base + o); pw[(q) & 1][bj] = *(const u32x4*)(pp + o); } } while (0)
;     __device__ __forceinline__ void operator()(f32x4 (&acc)[2][2][4][2], const Unit& u, int wr, int wc, int fr, int fq) const {
;     ...
;         bf16_t* hb = pp;
;         EP_LOAD(0); EP_LOAD(1); EP_ADD(0); EP_ADD(1);
; #pragma unroll
;         for (int q = 0; q < 8; q += 2) { if (q < 6) { EP_LOAD(q + 2); EP_LOAD(q + 3); } ER_STORE(q); ER_STORE(q + 1); if (q < 6) { EP_ADD(q + 2); EP_ADD(q + 3); } }
.LBB0_250:
	s_or_b64 exec, exec, s[12:13]
	v_ffbh_u32_e32 v32, v187
	v_min_u32_e32 v34, 32, v32
	s_waitcnt lgkmcnt(0)
	v_lshlrev_b64 v[32:33], v34, v[186:187]
	v_min_u32_e32 v32, 1, v32
	v_or_b32_e32 v32, v33, v32
	v_cvt_f32_u32_e32 v32, v32
	v_sub_u32_e32 v33, 32, v34
	s_waitcnt vmcnt(7)
	v_lshlrev_b32_e32 v34, 16, v76
	v_and_b32_e32 v35, 0xffff0000, v72
	v_ldexp_f32 v32, v32, v33
	v_fmamk_f32 v32, v32, 0x30800000, v223
	v_rsq_f32_e32 v32, v32
	v_lshlrev_b32_e32 v33, 16, v72
	v_and_b32_e32 v38, 0xffff0000, v76
	v_pk_mul_f32 v[28:29], v[28:29], v[32:33] op_sel_hi:[1,0]
	s_nop 0
	v_mul_f32_e32 v28, 0xbfb8aa3b, v28
	v_mul_f32_e32 v29, 0xbfb8aa3b, v29
	v_exp_f32_e32 v36, v28
	v_exp_f32_e32 v37, v29
	v_pk_mul_f32 v[28:29], v[30:31], v[32:33] op_sel_hi:[1,0]
	v_pk_mul_f32 v[24:25], v[24:25], v[32:33] op_sel_hi:[1,0]
	v_mul_f32_e32 v28, 0xbfb8aa3b, v28
	v_exp_f32_e32 v28, v28
	v_mul_f32_e32 v29, 0xbfb8aa3b, v29
	v_exp_f32_e32 v29, v29
	v_mul_f32_e32 v24, 0xbfb8aa3b, v24
	v_exp_f32_e32 v24, v24
	v_mul_f32_e32 v25, 0xbfb8aa3b, v25
	v_add_f32_e32 v30, 1.0, v36
	v_add_f32_e32 v31, 1.0, v37
	v_exp_f32_e32 v25, v25
	v_rcp_f32_e32 v30, v30
	v_rcp_f32_e32 v31, v31
	v_add_f32_e32 v28, 1.0, v28
	v_rcp_f32_e32 v28, v28
	v_add_f32_e32 v29, 1.0, v29
	v_rcp_f32_e32 v29, v29
	v_add_f32_e32 v24, 1.0, v24
	v_rcp_f32_e32 v24, v24
	v_add_f32_e32 v25, 1.0, v25
	v_pk_mul_f32 v[26:27], v[26:27], v[32:33] op_sel_hi:[1,0]
	v_fmac_f32_e32 v33, v30, v34
	v_fmac_f32_e32 v35, v31, v38
	v_lshlrev_b32_e32 v30, 16, v73
	v_lshlrev_b32_e32 v31, 16, v77
	v_rcp_f32_e32 v25, v25
	v_fmac_f32_e32 v30, v28, v31
	v_and_b32_e32 v28, 0xffff0000, v73
	v_and_b32_e32 v31, 0xffff0000, v77
	v_fmac_f32_e32 v28, v29, v31
	v_lshlrev_b32_e32 v29, 16, v74
	v_lshlrev_b32_e32 v31, 16, v78
	v_fmac_f32_e32 v29, v24, v31
	v_and_b32_e32 v24, 0xffff0000, v74
	v_and_b32_e32 v31, 0xffff0000, v78
	v_fmac_f32_e32 v24, v25, v31
	v_mul_f32_e32 v25, 0xbfb8aa3b, v26
	v_exp_f32_e32 v25, v25
	v_mul_f32_e32 v27, 0xbfb8aa3b, v27
	v_pk_mul_f32 v[20:21], v[20:21], v[32:33] op_sel_hi:[1,0]
	v_exp_f32_e32 v27, v27
	v_mul_f32_e32 v20, 0xbfb8aa3b, v20
	v_exp_f32_e32 v20, v20
	v_mul_f32_e32 v21, 0xbfb8aa3b, v21
	v_exp_f32_e32 v21, v21
	v_add_f32_e32 v25, 1.0, v25
	v_rcp_f32_e32 v25, v25
	v_add_f32_e32 v27, 1.0, v27
	v_rcp_f32_e32 v27, v27
	v_add_f32_e32 v20, 1.0, v20
	v_rcp_f32_e32 v20, v20
	v_add_f32_e32 v21, 1.0, v21
	v_lshlrev_b32_e32 v26, 16, v75
	v_lshlrev_b32_e32 v31, 16, v79
	v_rcp_f32_e32 v21, v21
	v_fmac_f32_e32 v26, v25, v31
	v_and_b32_e32 v25, 0xffff0000, v75
	v_and_b32_e32 v31, 0xffff0000, v79
	v_fmac_f32_e32 v25, v27, v31
	v_lshlrev_b32_e32 v27, 16, v64
	v_lshlrev_b32_e32 v31, 16, v68
	v_pk_mul_f32 v[22:23], v[22:23], v[32:33] op_sel_hi:[1,0]
	v_fmac_f32_e32 v27, v20, v31
	v_and_b32_e32 v20, 0xffff0000, v64
	v_and_b32_e32 v31, 0xffff0000, v68
	v_fmac_f32_e32 v20, v21, v31
	v_mul_f32_e32 v21, 0xbfb8aa3b, v22
	v_pk_mul_f32 v[16:17], v[16:17], v[32:33] op_sel_hi:[1,0]
	v_exp_f32_e32 v21, v21
	v_mul_f32_e32 v23, 0xbfb8aa3b, v23
	v_exp_f32_e32 v23, v23
	v_mul_f32_e32 v16, 0xbfb8aa3b, v16
	v_exp_f32_e32 v16, v16
	v_mul_f32_e32 v17, 0xbfb8aa3b, v17
	v_exp_f32_e32 v17, v17
	v_add_f32_e32 v21, 1.0, v21
	v_rcp_f32_e32 v21, v21
	v_add_f32_e32 v23, 1.0, v23
	v_rcp_f32_e32 v23, v23
	v_add_f32_e32 v16, 1.0, v16
	v_rcp_f32_e32 v16, v16
	v_add_f32_e32 v17, 1.0, v17
	v_lshlrev_b32_e32 v22, 16, v65
	v_lshlrev_b32_e32 v31, 16, v69
	v_rcp_f32_e32 v17, v17
	v_fmac_f32_e32 v22, v21, v31
	v_and_b32_e32 v21, 0xffff0000, v65
	v_and_b32_e32 v31, 0xffff0000, v69
	v_fmac_f32_e32 v21, v23, v31
	v_lshlrev_b32_e32 v23, 16, v66
	v_lshlrev_b32_e32 v31, 16, v70
	v_pk_mul_f32 v[18:19], v[18:19], v[32:33] op_sel_hi:[1,0]
	v_fmac_f32_e32 v23, v16, v31
	v_and_b32_e32 v31, 0xffff0000, v66
	v_and_b32_e32 v16, 0xffff0000, v70
	v_fmac_f32_e32 v31, v17, v16
	v_mul_f32_e32 v16, 0xbfb8aa3b, v18
	v_exp_f32_e32 v16, v16
	v_mul_f32_e32 v17, 0xbfb8aa3b, v19
	v_exp_f32_e32 v17, v17
	v_lshlrev_b32_e32 v32, 16, v67
	v_add_f32_e32 v16, 1.0, v16
	v_rcp_f32_e32 v16, v16
	v_add_f32_e32 v17, 1.0, v17
	v_rcp_f32_e32 v17, v17
	v_lshlrev_b32_e32 v18, 16, v71
	v_fmac_f32_e32 v32, v16, v18
	v_and_b32_e32 v34, 0xffff0000, v67
	v_and_b32_e32 v16, 0xffff0000, v71
	v_fmac_f32_e32 v34, v17, v16
	v_cvt_pk_bf16_f32 v16, v33, v35
	v_cvt_pk_bf16_f32 v17, v30, v28
	v_cvt_pk_bf16_f32 v18, v29, v24
	v_cvt_pk_bf16_f32 v19, v26, v25
	global_store_dwordx4 v[102:103], v[16:19], off sc1
	v_lshlrev_b32_e32 v24, 16, v16
	s_nop 0
	v_and_b32_e32 v16, 0xffff0000, v16
	v_mul_f32_e32 v16, v16, v16
	v_fmac_f32_e32 v16, v24, v24
	v_lshlrev_b32_e32 v24, 16, v17
	v_and_b32_e32 v17, 0xffff0000, v17
	v_mul_f32_e32 v17, v17, v17
	v_fmac_f32_e32 v17, v24, v24
	v_add_f32_e32 v16, v16, v17
	v_lshlrev_b32_e32 v17, 16, v18
	v_and_b32_e32 v18, 0xffff0000, v18
	v_mul_f32_e32 v18, v18, v18
	v_fmac_f32_e32 v18, v17, v17
	v_add_f32_e32 v16, v16, v18
	v_and_b32_e32 v18, 0xffff0000, v19
	v_lshlrev_b32_e32 v17, 16, v19
	v_mul_f32_e32 v18, v18, v18
	v_fmac_f32_e32 v18, v17, v17
	v_add_f32_e32 v16, v16, v18
	v_cvt_pk_bf16_f32 v18, v27, v20
	v_cvt_pk_bf16_f32 v19, v22, v21
	v_cvt_pk_bf16_f32 v20, v23, v31
	v_cvt_pk_bf16_f32 v21, v32, v34
	global_store_dwordx4 v[100:101], v[18:21], off sc1
	v_and_b32_e32 v22, 0xffff0000, v18
	v_lshlrev_b32_e32 v17, 16, v18
	v_mul_f32_e32 v22, v22, v22
	v_fmac_f32_e32 v22, v17, v17
	v_add_f32_e32 v16, v16, v22
	v_and_b32_e32 v22, 0xffff0000, v19
	v_lshlrev_b32_e32 v17, 16, v19
	v_mul_f32_e32 v22, v22, v22
	v_fmac_f32_e32 v22, v17, v17
	v_add_f32_e32 v16, v16, v22
	v_and_b32_e32 v22, 0xffff0000, v20
	v_lshlrev_b32_e32 v17, 16, v20
	v_mul_f32_e32 v22, v22, v22
	v_fmac_f32_e32 v22, v17, v17
	v_add_f32_e32 v16, v16, v22
	v_and_b32_e32 v22, 0xffff0000, v21
	v_lshlrev_b32_e32 v17, 16, v21
	v_mul_f32_e32 v22, v22, v22
	v_fmac_f32_e32 v22, v17, v17
	v_add_f32_e32 v16, v16, v22
	ds_bpermute_b32 v17, v191, v16
	s_waitcnt lgkmcnt(0)
	v_add_f32_e32 v16, v16, v17
	ds_bpermute_b32 v17, v214, v16
	s_and_saveexec_b64 s[12:13], vcc
	s_cbranch_execz .LBB0_252
	s_waitcnt lgkmcnt(0)
	v_add_f32_e32 v16, v16, v17
	v_mul_f32_e32 v16, 0x49800000, v16
	v_trunc_f32_e32 v16, v16
	v_mul_f32_e32 v17, 0x2f800000, v16
	v_floor_f32_e32 v17, v17
	v_fmac_f32_e32 v16, 0xcf800000, v17
	v_cvt_u32_f32_e32 v16, v16
	v_cvt_u32_f32_e32 v17, v17
	global_atomic_add_x2 v[192:193], v[16:17], off offset:1280
; #define EP_LOAD(q) do { _Pragma("unroll") for (int bj = 0; bj < 2; ++bj) { const unsigned o = ER_OFF(q, bj); t[(q) & 1][bj] = *(const u32x4*)(base + o); pw[(q) & 1][bj] = *(const u32x4*)(pp + o); } } while (0)
;     __device__ __forceinline__ void operator()(f32x4 (&acc)[2][2][4][2], const Unit& u, int wr, int wc, int fr, int fq) const {
;     ...
;         bf16_t* hb = pp;
;         EP_LOAD(0); EP_LOAD(1); EP_ADD(0); EP_ADD(1);
; #pragma unroll
;         for (int q = 0; q < 8; q += 2) { if (q < 6) { EP_LOAD(q + 2); EP_LOAD(q + 3); } ER_STORE(q); ER_STORE(q + 1); if (q < 6) { EP_ADD(q + 2); EP_ADD(q + 3); } }
.LBB0_252:
	s_or_b64 exec, exec, s[12:13]
	v_ffbh_u32_e32 v16, v167
	v_min_u32_e32 v18, 32, v16
	s_waitcnt lgkmcnt(0)
	v_lshlrev_b64 v[16:17], v18, v[166:167]
	v_min_u32_e32 v16, 1, v16
	v_or_b32_e32 v16, v17, v16
	v_cvt_f32_u32_e32 v16, v16
	v_sub_u32_e32 v17, 32, v18
	v_lshlrev_b32_e32 v18, 16, v60
	s_waitcnt vmcnt(8)
	v_and_b32_e32 v19, 0xffff0000, v56
	v_ldexp_f32 v16, v16, v17
	v_fmamk_f32 v16, v16, 0x30800000, v223
	v_rsq_f32_e32 v16, v16
	v_lshlrev_b32_e32 v17, 16, v56
	v_and_b32_e32 v22, 0xffff0000, v60
	v_pk_mul_f32 v[12:13], v[12:13], v[16:17] op_sel_hi:[1,0]
	s_nop 0
	v_mul_f32_e32 v12, 0xbfb8aa3b, v12
	v_mul_f32_e32 v13, 0xbfb8aa3b, v13
	v_exp_f32_e32 v20, v12
	v_exp_f32_e32 v21, v13
	v_pk_mul_f32 v[12:13], v[14:15], v[16:17] op_sel_hi:[1,0]
	v_pk_mul_f32 v[8:9], v[8:9], v[16:17] op_sel_hi:[1,0]
	v_mul_f32_e32 v12, 0xbfb8aa3b, v12
	v_exp_f32_e32 v12, v12
	v_mul_f32_e32 v13, 0xbfb8aa3b, v13
	v_exp_f32_e32 v13, v13
	v_mul_f32_e32 v8, 0xbfb8aa3b, v8
	v_exp_f32_e32 v8, v8
	v_mul_f32_e32 v9, 0xbfb8aa3b, v9
	v_add_f32_e32 v14, 1.0, v20
	v_add_f32_e32 v15, 1.0, v21
	v_exp_f32_e32 v9, v9
	v_rcp_f32_e32 v14, v14
	v_rcp_f32_e32 v15, v15
	v_add_f32_e32 v12, 1.0, v12
	v_rcp_f32_e32 v12, v12
	v_add_f32_e32 v13, 1.0, v13
	v_rcp_f32_e32 v13, v13
	v_add_f32_e32 v8, 1.0, v8
	v_rcp_f32_e32 v8, v8
	v_add_f32_e32 v9, 1.0, v9
	v_pk_mul_f32 v[10:11], v[10:11], v[16:17] op_sel_hi:[1,0]
	v_fmac_f32_e32 v17, v14, v18
	v_fmac_f32_e32 v19, v15, v22
	v_lshlrev_b32_e32 v14, 16, v57
	v_lshlrev_b32_e32 v15, 16, v61
	v_rcp_f32_e32 v9, v9
	v_fmac_f32_e32 v14, v12, v15
	v_and_b32_e32 v12, 0xffff0000, v57
	v_and_b32_e32 v15, 0xffff0000, v61
	v_fmac_f32_e32 v12, v13, v15
	v_lshlrev_b32_e32 v13, 16, v58
	v_lshlrev_b32_e32 v15, 16, v62
	v_fmac_f32_e32 v13, v8, v15
	v_and_b32_e32 v8, 0xffff0000, v58
	v_and_b32_e32 v15, 0xffff0000, v62
	v_fmac_f32_e32 v8, v9, v15
	v_mul_f32_e32 v9, 0xbfb8aa3b, v10
	v_exp_f32_e32 v9, v9
	v_mul_f32_e32 v11, 0xbfb8aa3b, v11
	v_pk_mul_f32 v[4:5], v[4:5], v[16:17] op_sel_hi:[1,0]
	v_exp_f32_e32 v11, v11
	v_mul_f32_e32 v4, 0xbfb8aa3b, v4
	v_exp_f32_e32 v4, v4
	v_mul_f32_e32 v5, 0xbfb8aa3b, v5
	v_exp_f32_e32 v5, v5
	v_add_f32_e32 v9, 1.0, v9
	v_rcp_f32_e32 v9, v9
	v_add_f32_e32 v11, 1.0, v11
	v_rcp_f32_e32 v11, v11
	v_add_f32_e32 v4, 1.0, v4
	v_rcp_f32_e32 v4, v4
	v_add_f32_e32 v5, 1.0, v5
	v_lshlrev_b32_e32 v10, 16, v59
	v_lshlrev_b32_e32 v15, 16, v63
	v_rcp_f32_e32 v5, v5
	v_fmac_f32_e32 v10, v9, v15
	v_and_b32_e32 v9, 0xffff0000, v59
	v_and_b32_e32 v15, 0xffff0000, v63
	v_fmac_f32_e32 v9, v11, v15
	s_waitcnt vmcnt(6)
	v_lshlrev_b32_e32 v11, 16, v48
	v_lshlrev_b32_e32 v15, 16, v52
	v_pk_mul_f32 v[6:7], v[6:7], v[16:17] op_sel_hi:[1,0]
	v_fmac_f32_e32 v11, v4, v15
	v_and_b32_e32 v4, 0xffff0000, v48
	v_and_b32_e32 v15, 0xffff0000, v52
	v_fmac_f32_e32 v4, v5, v15
	v_mul_f32_e32 v5, 0xbfb8aa3b, v6
	v_pk_mul_f32 v[0:1], v[0:1], v[16:17] op_sel_hi:[1,0]
	v_exp_f32_e32 v5, v5
	v_mul_f32_e32 v7, 0xbfb8aa3b, v7
	v_exp_f32_e32 v7, v7
	v_mul_f32_e32 v0, 0xbfb8aa3b, v0
	v_exp_f32_e32 v0, v0
	v_mul_f32_e32 v1, 0xbfb8aa3b, v1
	v_exp_f32_e32 v1, v1
	v_add_f32_e32 v5, 1.0, v5
	v_rcp_f32_e32 v5, v5
	v_add_f32_e32 v7, 1.0, v7
	v_rcp_f32_e32 v7, v7
	v_add_f32_e32 v0, 1.0, v0
	v_rcp_f32_e32 v0, v0
	v_add_f32_e32 v1, 1.0, v1
	v_lshlrev_b32_e32 v6, 16, v49
	v_lshlrev_b32_e32 v15, 16, v53
	v_rcp_f32_e32 v1, v1
	v_fmac_f32_e32 v6, v5, v15
	v_and_b32_e32 v5, 0xffff0000, v49
	v_and_b32_e32 v15, 0xffff0000, v53
	v_fmac_f32_e32 v5, v7, v15
	v_lshlrev_b32_e32 v7, 16, v50
	v_lshlrev_b32_e32 v15, 16, v54
	v_pk_mul_f32 v[2:3], v[2:3], v[16:17] op_sel_hi:[1,0]
	v_fmac_f32_e32 v7, v0, v15
	v_and_b32_e32 v15, 0xffff0000, v50
	v_and_b32_e32 v0, 0xffff0000, v54
	v_fmac_f32_e32 v15, v1, v0
	v_mul_f32_e32 v0, 0xbfb8aa3b, v2
	v_exp_f32_e32 v0, v0
	v_mul_f32_e32 v1, 0xbfb8aa3b, v3
	v_exp_f32_e32 v1, v1
	v_lshlrev_b32_e32 v16, 16, v51
	v_add_f32_e32 v0, 1.0, v0
	v_rcp_f32_e32 v0, v0
	v_add_f32_e32 v1, 1.0, v1
	v_rcp_f32_e32 v1, v1
	v_lshlrev_b32_e32 v2, 16, v55
	v_fmac_f32_e32 v16, v0, v2
	v_and_b32_e32 v18, 0xffff0000, v51
	v_and_b32_e32 v0, 0xffff0000, v55
	v_fmac_f32_e32 v18, v1, v0
	v_cvt_pk_bf16_f32 v0, v17, v19
	v_cvt_pk_bf16_f32 v1, v14, v12
	v_cvt_pk_bf16_f32 v2, v13, v8
	v_cvt_pk_bf16_f32 v3, v10, v9
	global_store_dwordx4 v[98:99], v[0:3], off sc1
	v_lshlrev_b32_e32 v8, 16, v0
	s_nop 0
	v_and_b32_e32 v0, 0xffff0000, v0
	v_mul_f32_e32 v0, v0, v0
	v_fmac_f32_e32 v0, v8, v8
	v_lshlrev_b32_e32 v8, 16, v1
	v_and_b32_e32 v1, 0xffff0000, v1
	v_mul_f32_e32 v1, v1, v1
	v_fmac_f32_e32 v1, v8, v8
	v_add_f32_e32 v0, v0, v1
	v_lshlrev_b32_e32 v1, 16, v2
	v_and_b32_e32 v2, 0xffff0000, v2
	v_mul_f32_e32 v2, v2, v2
	v_fmac_f32_e32 v2, v1, v1
	v_add_f32_e32 v0, v0, v2
	v_and_b32_e32 v2, 0xffff0000, v3
	v_lshlrev_b32_e32 v1, 16, v3
	v_mul_f32_e32 v2, v2, v2
	v_fmac_f32_e32 v2, v1, v1
	v_add_f32_e32 v0, v0, v2
	v_cvt_pk_bf16_f32 v2, v11, v4
	v_cvt_pk_bf16_f32 v3, v6, v5
	v_cvt_pk_bf16_f32 v4, v7, v15
	v_cvt_pk_bf16_f32 v5, v16, v18
	global_store_dwordx4 v[96:97], v[2:5], off sc1
	v_and_b32_e32 v6, 0xffff0000, v2
	v_lshlrev_b32_e32 v1, 16, v2
	v_mul_f32_e32 v6, v6, v6
	v_fmac_f32_e32 v6, v1, v1
	v_add_f32_e32 v0, v0, v6
	v_and_b32_e32 v6, 0xffff0000, v3
	v_lshlrev_b32_e32 v1, 16, v3
	v_mul_f32_e32 v6, v6, v6
	v_fmac_f32_e32 v6, v1, v1
	v_add_f32_e32 v0, v0, v6
	v_and_b32_e32 v6, 0xffff0000, v4
	v_lshlrev_b32_e32 v1, 16, v4
	v_mul_f32_e32 v6, v6, v6
	v_fmac_f32_e32 v6, v1, v1
	v_add_f32_e32 v0, v0, v6
	v_and_b32_e32 v6, 0xffff0000, v5
	v_lshlrev_b32_e32 v1, 16, v5
	v_mul_f32_e32 v6, v6, v6
	v_fmac_f32_e32 v6, v1, v1
	v_add_f32_e32 v0, v0, v6
	ds_bpermute_b32 v1, v191, v0
	s_waitcnt lgkmcnt(0)
	v_add_f32_e32 v0, v0, v1
	ds_bpermute_b32 v1, v214, v0
	s_and_saveexec_b64 s[12:13], vcc
	s_cbranch_execz .LBB0_227
	s_waitcnt lgkmcnt(0)
	v_add_f32_e32 v0, v0, v1
	v_mul_f32_e32 v0, 0x49800000, v0
	v_trunc_f32_e32 v0, v0
	v_mul_f32_e32 v1, 0x2f800000, v0
	v_floor_f32_e32 v1, v1
	v_fmac_f32_e32 v0, 0xcf800000, v1
	v_cvt_u32_f32_e32 v0, v0
	v_cvt_u32_f32_e32 v1, v1
	global_atomic_add_x2 v[192:193], v[0:1], off offset:1408
	s_branch .LBB0_227

; #define ER_LOAD(q) do { _Pragma("unroll") for (int bj = 0; bj < 2; ++bj) t[(q) & 3][bj] = *(const u32x4*)(base + ER_OFF(q, bj)); } while (0)
; #define ER_ADD(q) do { _Pragma("unroll") for (int bj = 0; bj < 2; ++bj) { f32x4& a0 = acc[(q) >> 2][bj][(q) & 3][0]; f32x4& a1 = acc[(q) >> 2][bj][(q) & 3][1]; const u32x4 p = t[(q) & 3][bj]; \
;             a0[0] += bf_lo(p.x); a0[1] += bf_hi(p.x); a0[2] += bf_lo(p.y); a0[3] += bf_hi(p.y); a1[0] += bf_lo(p.z); a1[1] += bf_hi(p.z); a1[2] += bf_lo(p.w); a1[3] += bf_hi(p.w); } } while (0)
;     __device__ __forceinline__ void operator()(f32x4 (&acc)[2][2][4][2], const Unit& u, int wr, int wc, int fr, int fq) const {
;         const int row0 = u.pm * BM + wr * 64 + fr, col0 = u.pn * BM + wc * 32 + 8 * fq; const unsigned off0 = (unsigned)row0 * 1024u + (unsigned)col0;
;         u32x4 t[4][2];
;     ...
; #pragma unroll
;         for (int q = 0; q < 4; ++q) ER_LOAD(q);
; #pragma unroll
;         for (int q = 0; q < 4; ++q) ER_ADD(q);
; #pragma unroll
;         for (int q = 4; q < 8; ++q) ER_LOAD(q);
; #pragma unroll
;         for (int q = 0; q < 4; ++q) ER_STORE(q);
; #pragma unroll
;         for (int q = 4; q < 8; ++q) { ER_ADD(q); ER_STORE(q); }
.LBB0_276:
	v_mov_b32_e32 v128, v170
	s_lshl_b32 s11, s67, 8
	v_readfirstlane_b32 s10, v128
	s_ashr_i32 s14, s10, 2
	s_andn2_b32 s14, s14, 63
	s_lshr_b32 s10, s10, 1
	s_add_i32 s14, s14, s11
	s_lshl_b32 s11, s66, 8
	s_and_b32 s10, s10, 0x60
	v_bfe_u32 v173, v128, 4, 2
	s_or_b32 s10, s10, s11
	v_and_or_b32 v218, v128, 15, s14
	v_lshl_or_b32 v128, v173, 3, s10
	v_lshl_add_u32 v140, v218, 10, v128
	v_mov_b32_e32 v141, v169
	v_lshlrev_b64 v[220:221], 1, v[140:141]
	v_lshl_add_u64 v[132:133], v[176:177], 0, v[220:221]
	global_load_dwordx4 v[128:131], v[132:133], off
	global_load_dwordx4 v[142:145], v[132:133], off offset:256
	v_add_u32_e32 v168, 0x4000, v140
	v_add_u32_e32 v202, 0x20000, v140
	v_mov_b32_e32 v203, v169
	v_lshl_add_u64 v[132:133], v[168:169], 1, v[176:177]
	v_add_u32_e32 v216, 0x4080, v140
	v_mov_b32_e32 v217, v169
	v_add_u32_e32 v210, 0x20080, v140
	v_mov_b32_e32 v211, v169
	global_load_dwordx4 v[160:163], v[132:133], off
	v_add_u32_e32 v214, 0x8000, v140
	v_mov_b32_e32 v215, v169
	v_add_u32_e32 v206, 0x24000, v140
	v_mov_b32_e32 v207, v169
	v_add_u32_e32 v212, 0x8080, v140
	v_mov_b32_e32 v213, v169
	v_add_u32_e32 v200, 0x24080, v140
	v_mov_b32_e32 v201, v169
	v_add_u32_e32 v208, 0xc000, v140
	v_mov_b32_e32 v209, v169
	v_add_u32_e32 v198, 0x28000, v140
	v_mov_b32_e32 v199, v169
	v_add_u32_e32 v204, 0xc080, v140
	v_mov_b32_e32 v205, v169
	v_add_u32_e32 v196, 0x28080, v140
	v_mov_b32_e32 v197, v169
	v_lshl_add_u64 v[136:137], v[204:205], 1, v[176:177]
	v_add_u32_e32 v194, 0x2c000, v140
	v_mov_b32_e32 v195, v169
	v_add_u32_e32 v192, 0x2c080, v140
	v_mov_b32_e32 v193, v169
	global_load_dwordx4 v[136:139], v[136:137], off
	v_cmp_eq_u32_e32 vcc, 0, v173
	v_lshl_add_u64 v[220:221], s[42:43], 0, v[220:221]
	v_cmp_lt_i32_e64 s[10:11], v233, v228
	v_ashrrev_i32_e32 v219, 31, v218
	v_lshl_add_u64 v[218:219], v[218:219], 3, s[40:41]
	s_waitcnt vmcnt(0)
	v_lshlrev_b32_e32 v141, 16, v128
	v_add_f32_e32 v248, v124, v141
	v_and_b32_e32 v124, 0xffff0000, v128
	v_add_f32_e32 v249, v125, v124
	v_lshlrev_b32_e32 v124, 16, v129
	v_add_f32_e32 v250, v126, v124
	v_and_b32_e32 v124, 0xffff0000, v129
	v_add_f32_e32 v251, v127, v124
	v_lshlrev_b32_e32 v124, 16, v130
	v_add_f32_e32 v252, v120, v124
	v_and_b32_e32 v120, 0xffff0000, v130
	v_add_f32_e32 v253, v121, v120
	v_lshlrev_b32_e32 v120, 16, v131
	v_add_f32_e32 v254, v122, v120
	v_and_b32_e32 v120, 0xffff0000, v131
	v_add_f32_e32 v237, v123, v120
	v_lshlrev_b32_e32 v120, 16, v142
	v_add_f32_e32 v240, v116, v120
	v_and_b32_e32 v116, 0xffff0000, v142
	v_add_f32_e32 v241, v117, v116
	v_lshlrev_b32_e32 v116, 16, v143
	v_add_f32_e32 v242, v118, v116
	v_and_b32_e32 v116, 0xffff0000, v143
	v_add_f32_e32 v243, v119, v116
	v_lshlrev_b32_e32 v116, 16, v144
	v_add_f32_e32 v244, v112, v116
	v_and_b32_e32 v112, 0xffff0000, v144
	v_add_f32_e32 v245, v113, v112
	v_lshlrev_b32_e32 v112, 16, v145
	v_add_f32_e32 v246, v114, v112
	v_and_b32_e32 v112, 0xffff0000, v145
	v_add_f32_e32 v247, v115, v112
	v_lshl_add_u64 v[112:113], v[202:203], 1, v[176:177]
	global_load_dwordx4 v[144:147], v[112:113], off
	v_lshl_add_u64 v[132:133], v[216:217], 1, v[176:177]
	v_lshl_add_u64 v[112:113], v[210:211], 1, v[176:177]
	global_load_dwordx4 v[164:167], v[132:133], off
	global_load_dwordx4 v[148:151], v[112:113], off
	v_lshl_add_u64 v[132:133], v[214:215], 1, v[176:177]
	v_lshl_add_u64 v[112:113], v[206:207], 1, v[176:177]
	global_load_dwordx4 v[152:155], v[132:133], off
	global_load_dwordx4 v[124:127], v[112:113], off
	v_lshl_add_u64 v[132:133], v[212:213], 1, v[176:177]
	v_lshl_add_u64 v[112:113], v[200:201], 1, v[176:177]
	global_load_dwordx4 v[156:159], v[132:133], off
	global_load_dwordx4 v[128:131], v[112:113], off
	v_lshl_add_u64 v[132:133], v[208:209], 1, v[176:177]
	v_lshl_add_u64 v[112:113], v[198:199], 1, v[176:177]
	global_load_dwordx4 v[132:135], v[132:133], off
	v_lshl_add_u64 v[140:141], v[192:193], 1, v[176:177]
	global_load_dwordx4 v[116:119], v[112:113], off
	v_lshl_add_u64 v[112:113], v[196:197], 1, v[176:177]
	global_load_dwordx4 v[120:123], v[112:113], off
	v_lshl_add_u64 v[112:113], v[194:195], 1, v[176:177]
	global_load_dwordx4 v[112:115], v[112:113], off
	s_nop 0
	global_load_dwordx4 v[140:143], v[140:141], off
	v_cvt_pk_bf16_f32 v248, v248, v249
	v_cvt_pk_bf16_f32 v249, v250, v251
	v_cvt_pk_bf16_f32 v250, v252, v253
	v_cvt_pk_bf16_f32 v251, v254, v237
	global_store_dwordx4 v[220:221], v[248:251], off sc1
	v_and_b32_e32 v226, 0xffff0000, v248
	v_lshlrev_b32_e32 v173, 16, v248
	v_mul_f32_e32 v226, v226, v226
	v_and_b32_e32 v227, 0xffff0000, v249
	v_fmac_f32_e32 v226, v173, v173
	v_lshlrev_b32_e32 v173, 16, v249
	v_mul_f32_e32 v227, v227, v227
	v_fmac_f32_e32 v227, v173, v173
	v_add_f32_e32 v173, v226, v227
	v_and_b32_e32 v227, 0xffff0000, v250
	v_lshlrev_b32_e32 v226, 16, v250
	v_mul_f32_e32 v227, v227, v227
	v_fmac_f32_e32 v227, v226, v226
	v_add_f32_e32 v173, v173, v227
	v_and_b32_e32 v227, 0xffff0000, v251
	v_lshlrev_b32_e32 v226, 16, v251
	v_mul_f32_e32 v227, v227, v227
	v_cvt_pk_bf16_f32 v240, v240, v241
	v_cvt_pk_bf16_f32 v241, v242, v243
	v_cvt_pk_bf16_f32 v242, v244, v245
	v_cvt_pk_bf16_f32 v243, v246, v247
	global_store_dwordx4 v[220:221], v[240:243], off offset:256 sc1
	v_and_b32_e32 v221, 0xffff0000, v240
	v_fmac_f32_e32 v227, v226, v226
	v_lshlrev_b32_e32 v220, 16, v240
	v_mul_f32_e32 v221, v221, v221
	v_add_f32_e32 v173, v173, v227
	v_fmac_f32_e32 v221, v220, v220
	v_add_f32_e32 v173, v173, v221
	v_and_b32_e32 v221, 0xffff0000, v241
	v_lshlrev_b32_e32 v220, 16, v241
	v_mul_f32_e32 v221, v221, v221
	v_fmac_f32_e32 v221, v220, v220
	v_add_f32_e32 v173, v173, v221
	v_and_b32_e32 v221, 0xffff0000, v242
	v_lshlrev_b32_e32 v220, 16, v242
	v_mul_f32_e32 v221, v221, v221
	v_fmac_f32_e32 v221, v220, v220
	v_add_f32_e32 v173, v173, v221
	v_and_b32_e32 v221, 0xffff0000, v243
	v_lshlrev_b32_e32 v220, 16, v243
	v_mul_f32_e32 v221, v221, v221
	v_fmac_f32_e32 v221, v220, v220
	v_add_f32_e32 v220, v173, v221
	v_cndmask_b32_e64 v173, v225, v233, s[10:11]
	v_lshlrev_b32_e32 v173, 2, v173
	ds_bpermute_b32 v221, v173, v220
	v_cmp_lt_i32_e64 s[10:11], v234, v228
	s_waitcnt lgkmcnt(0)
	v_add_f32_e32 v221, v220, v221
	v_cndmask_b32_e64 v220, v225, v234, s[10:11]
	v_lshlrev_b32_e32 v220, 2, v220
	ds_bpermute_b32 v237, v220, v221
	s_and_saveexec_b64 s[10:11], vcc
	s_cbranch_execz .LBB0_278
	s_waitcnt lgkmcnt(0)
	v_add_f32_e32 v221, v221, v237
	v_mul_f32_e32 v221, 0x49800000, v221
	v_trunc_f32_e32 v221, v221
	v_mul_f32_e32 v226, 0x2f800000, v221
	v_floor_f32_e32 v227, v226
	v_fmac_f32_e32 v221, 0xcf800000, v227
	v_cvt_u32_f32_e32 v226, v221
	v_cvt_u32_f32_e32 v227, v227
	global_atomic_add_x2 v[218:219], v[226:227], off
.LBB0_278:
	s_or_b64 exec, exec, s[10:11]
	v_lshlrev_b32_e32 v221, 16, v160
	v_and_b32_e32 v160, 0xffff0000, v160
	v_add_f32_e32 v109, v109, v160
	v_lshlrev_b32_e32 v160, 16, v161
	v_add_f32_e32 v110, v110, v160
	v_and_b32_e32 v160, 0xffff0000, v161
	v_add_f32_e32 v111, v111, v160
	v_lshlrev_b32_e32 v160, 16, v162
	v_add_f32_e32 v104, v104, v160
	v_and_b32_e32 v160, 0xffff0000, v162
	v_add_f32_e32 v105, v105, v160
	v_lshlrev_b32_e32 v160, 16, v163
	v_add_f32_e32 v106, v106, v160
	v_and_b32_e32 v160, 0xffff0000, v163
	v_add_f32_e32 v107, v107, v160
	s_waitcnt vmcnt(12)
	v_lshlrev_b32_e32 v160, 16, v164
	v_add_f32_e32 v160, v100, v160
	v_and_b32_e32 v100, 0xffff0000, v164
	v_add_f32_e32 v161, v101, v100
	v_lshlrev_b32_e32 v100, 16, v165
	v_add_f32_e32 v102, v102, v100
	v_and_b32_e32 v100, 0xffff0000, v165
	v_add_f32_e32 v103, v103, v100
	v_lshlrev_b32_e32 v100, 16, v166
	v_add_f32_e32 v162, v96, v100
	v_and_b32_e32 v96, 0xffff0000, v166
	v_add_f32_e32 v163, v97, v96
	v_lshlrev_b32_e32 v96, 16, v167
	v_add_f32_e32 v164, v98, v96
	v_and_b32_e32 v96, 0xffff0000, v167
	v_add_f32_e32 v108, v108, v221
	v_add_f32_e32 v165, v99, v96
	v_cvt_pk_bf16_f32 v96, v108, v109
	v_lshl_add_u64 v[100:101], v[168:169], 1, s[42:43]
	v_cvt_pk_bf16_f32 v97, v110, v111
	v_cvt_pk_bf16_f32 v98, v104, v105
	v_cvt_pk_bf16_f32 v99, v106, v107
	global_store_dwordx4 v[100:101], v[96:99], off sc1
	v_lshlrev_b32_e32 v100, 16, v96
	s_nop 0
	v_and_b32_e32 v96, 0xffff0000, v96
	v_mul_f32_e32 v96, v96, v96
	v_fmac_f32_e32 v96, v100, v100
	v_lshlrev_b32_e32 v100, 16, v97
	v_and_b32_e32 v97, 0xffff0000, v97
	v_mul_f32_e32 v97, v97, v97
	v_fmac_f32_e32 v97, v100, v100
	v_add_f32_e32 v96, v96, v97
	v_lshlrev_b32_e32 v97, 16, v98
	v_and_b32_e32 v98, 0xffff0000, v98
	v_mul_f32_e32 v98, v98, v98
	v_fmac_f32_e32 v98, v97, v97
	v_add_f32_e32 v96, v96, v98
	v_and_b32_e32 v98, 0xffff0000, v99
	v_lshlrev_b32_e32 v97, 16, v99
	v_mul_f32_e32 v98, v98, v98
	v_fmac_f32_e32 v98, v97, v97
	v_add_f32_e32 v96, v96, v98
	v_cvt_pk_bf16_f32 v98, v160, v161
	v_cvt_pk_bf16_f32 v99, v102, v103
	v_cvt_pk_bf16_f32 v100, v162, v163
	v_cvt_pk_bf16_f32 v101, v164, v165
	s_nop 0
	v_and_b32_e32 v102, 0xffff0000, v98
	v_lshlrev_b32_e32 v97, 16, v98
	v_mul_f32_e32 v102, v102, v102
	v_fmac_f32_e32 v102, v97, v97
	v_add_f32_e32 v96, v96, v102
	v_and_b32_e32 v102, 0xffff0000, v99
	v_lshlrev_b32_e32 v97, 16, v99
	v_mul_f32_e32 v102, v102, v102
	v_fmac_f32_e32 v102, v97, v97
	v_add_f32_e32 v96, v96, v102
	v_and_b32_e32 v102, 0xffff0000, v100
	v_lshlrev_b32_e32 v97, 16, v100
	v_mul_f32_e32 v102, v102, v102
	v_fmac_f32_e32 v102, v97, v97
	v_add_f32_e32 v96, v96, v102
	v_and_b32_e32 v102, 0xffff0000, v101
	v_lshlrev_b32_e32 v97, 16, v101
	v_mul_f32_e32 v102, v102, v102
	v_fmac_f32_e32 v102, v97, v97
	v_add_f32_e32 v96, v96, v102
	ds_bpermute_b32 v97, v173, v96
	v_lshl_add_u64 v[102:103], v[216:217], 1, s[42:43]
	global_store_dwordx4 v[102:103], v[98:101], off sc1
	s_waitcnt lgkmcnt(0)
	v_add_f32_e32 v96, v96, v97
	ds_bpermute_b32 v97, v220, v96
	s_and_saveexec_b64 s[10:11], vcc
	s_cbranch_execz .LBB0_280
	s_waitcnt lgkmcnt(0)
	v_add_f32_e32 v96, v96, v97
	v_mul_f32_e32 v96, 0x49800000, v96
	v_trunc_f32_e32 v96, v96
	v_mul_f32_e32 v97, 0x2f800000, v96
	v_floor_f32_e32 v97, v97
	v_fmac_f32_e32 v96, 0xcf800000, v97
	v_cvt_u32_f32_e32 v96, v96
	v_cvt_u32_f32_e32 v97, v97
	global_atomic_add_x2 v[218:219], v[96:97], off offset:128
.LBB0_280:
	s_or_b64 exec, exec, s[10:11]
	s_waitcnt vmcnt(12)
	v_lshlrev_b32_e32 v96, 16, v152
	v_add_f32_e32 v92, v92, v96
	v_and_b32_e32 v96, 0xffff0000, v152
	v_add_f32_e32 v93, v93, v96
	v_lshlrev_b32_e32 v96, 16, v153
	v_add_f32_e32 v94, v94, v96
	v_and_b32_e32 v96, 0xffff0000, v153
	v_add_f32_e32 v95, v95, v96
	v_lshlrev_b32_e32 v96, 16, v154
	v_add_f32_e32 v88, v88, v96
	v_and_b32_e32 v96, 0xffff0000, v154
	v_add_f32_e32 v89, v89, v96
	v_lshlrev_b32_e32 v96, 16, v155
	v_add_f32_e32 v90, v90, v96
	v_and_b32_e32 v96, 0xffff0000, v155
	v_add_f32_e32 v91, v91, v96
	s_waitcnt vmcnt(10)
	v_lshlrev_b32_e32 v96, 16, v156
	v_add_f32_e32 v96, v84, v96
	v_and_b32_e32 v84, 0xffff0000, v156
	s_waitcnt lgkmcnt(0)
	v_add_f32_e32 v97, v85, v84
	v_lshlrev_b32_e32 v84, 16, v157
	v_add_f32_e32 v86, v86, v84
	v_and_b32_e32 v84, 0xffff0000, v157
	v_add_f32_e32 v87, v87, v84
	v_lshlrev_b32_e32 v84, 16, v158
	v_add_f32_e32 v98, v80, v84
	v_and_b32_e32 v80, 0xffff0000, v158
	v_add_f32_e32 v99, v81, v80
	v_lshlrev_b32_e32 v80, 16, v159
	v_add_f32_e32 v100, v82, v80
	v_and_b32_e32 v80, 0xffff0000, v159
	v_add_f32_e32 v101, v83, v80
	v_cvt_pk_bf16_f32 v80, v92, v93
	v_lshl_add_u64 v[84:85], v[214:215], 1, s[42:43]
	v_cvt_pk_bf16_f32 v81, v94, v95
	v_cvt_pk_bf16_f32 v82, v88, v89
	v_cvt_pk_bf16_f32 v83, v90, v91
	global_store_dwordx4 v[84:85], v[80:83], off sc1
	v_lshlrev_b32_e32 v84, 16, v80
	s_nop 0
	v_and_b32_e32 v80, 0xffff0000, v80
	v_mul_f32_e32 v80, v80, v80
	v_fmac_f32_e32 v80, v84, v84
	v_lshlrev_b32_e32 v84, 16, v81
	v_and_b32_e32 v81, 0xffff0000, v81
	v_mul_f32_e32 v81, v81, v81
	v_fmac_f32_e32 v81, v84, v84
	v_add_f32_e32 v80, v80, v81
	v_lshlrev_b32_e32 v81, 16, v82
	v_and_b32_e32 v82, 0xffff0000, v82
	v_mul_f32_e32 v82, v82, v82
	v_fmac_f32_e32 v82, v81, v81
	v_add_f32_e32 v80, v80, v82
	v_and_b32_e32 v82, 0xffff0000, v83
	v_lshlrev_b32_e32 v81, 16, v83
	v_mul_f32_e32 v82, v82, v82
	v_fmac_f32_e32 v82, v81, v81
	v_add_f32_e32 v80, v80, v82
	v_cvt_pk_bf16_f32 v82, v96, v97
	v_cvt_pk_bf16_f32 v83, v86, v87
	v_cvt_pk_bf16_f32 v84, v98, v99
	v_cvt_pk_bf16_f32 v85, v100, v101
	s_nop 0
	v_and_b32_e32 v86, 0xffff0000, v82
	v_lshlrev_b32_e32 v81, 16, v82
	v_mul_f32_e32 v86, v86, v86
	v_fmac_f32_e32 v86, v81, v81
	v_add_f32_e32 v80, v80, v86
	v_and_b32_e32 v86, 0xffff0000, v83
	v_lshlrev_b32_e32 v81, 16, v83
	v_mul_f32_e32 v86, v86, v86
	v_fmac_f32_e32 v86, v81, v81
	v_add_f32_e32 v80, v80, v86
	v_and_b32_e32 v86, 0xffff0000, v84
	v_lshlrev_b32_e32 v81, 16, v84
	v_mul_f32_e32 v86, v86, v86
	v_fmac_f32_e32 v86, v81, v81
	v_add_f32_e32 v80, v80, v86
	v_and_b32_e32 v86, 0xffff0000, v85
	v_lshlrev_b32_e32 v81, 16, v85
	v_mul_f32_e32 v86, v86, v86
	v_fmac_f32_e32 v86, v81, v81
	v_add_f32_e32 v80, v80, v86
	ds_bpermute_b32 v81, v173, v80
	v_lshl_add_u64 v[86:87], v[212:213], 1, s[42:43]
	global_store_dwordx4 v[86:87], v[82:85], off sc1
	s_waitcnt lgkmcnt(0)
	v_add_f32_e32 v80, v80, v81
	ds_bpermute_b32 v81, v220, v80
	s_and_saveexec_b64 s[10:11], vcc
	s_cbranch_execz .LBB0_282
	s_waitcnt lgkmcnt(0)
	v_add_f32_e32 v80, v80, v81
	v_mul_f32_e32 v80, 0x49800000, v80
	v_trunc_f32_e32 v80, v80
	v_mul_f32_e32 v81, 0x2f800000, v80
	v_floor_f32_e32 v81, v81
	v_fmac_f32_e32 v80, 0xcf800000, v81
	v_cvt_u32_f32_e32 v80, v80
	v_cvt_u32_f32_e32 v81, v81
	global_atomic_add_x2 v[218:219], v[80:81], off offset:256
.LBB0_282:
	s_or_b64 exec, exec, s[10:11]
	s_waitcnt vmcnt(10)
	v_lshlrev_b32_e32 v80, 16, v132
	v_add_f32_e32 v76, v76, v80
	v_and_b32_e32 v80, 0xffff0000, v132
	v_add_f32_e32 v77, v77, v80
	v_lshlrev_b32_e32 v80, 16, v133
	v_add_f32_e32 v78, v78, v80
	v_and_b32_e32 v80, 0xffff0000, v133
	v_add_f32_e32 v79, v79, v80
	v_lshlrev_b32_e32 v80, 16, v134
	v_add_f32_e32 v72, v72, v80
	v_and_b32_e32 v80, 0xffff0000, v134
	v_add_f32_e32 v73, v73, v80
	v_lshlrev_b32_e32 v80, 16, v135
	v_add_f32_e32 v74, v74, v80
	v_and_b32_e32 v80, 0xffff0000, v135
	v_add_f32_e32 v75, v75, v80
	v_lshlrev_b32_e32 v80, 16, v136
	v_add_f32_e32 v80, v68, v80
	v_and_b32_e32 v68, 0xffff0000, v136
	s_waitcnt lgkmcnt(0)
	v_add_f32_e32 v81, v69, v68
	v_lshlrev_b32_e32 v68, 16, v137
	v_add_f32_e32 v70, v70, v68
	v_and_b32_e32 v68, 0xffff0000, v137
	v_add_f32_e32 v71, v71, v68
	v_lshlrev_b32_e32 v68, 16, v138
	v_add_f32_e32 v82, v64, v68
	v_and_b32_e32 v64, 0xffff0000, v138
	v_add_f32_e32 v83, v65, v64
	v_lshlrev_b32_e32 v64, 16, v139
	v_add_f32_e32 v84, v66, v64
	v_and_b32_e32 v64, 0xffff0000, v139
	v_add_f32_e32 v85, v67, v64
	v_cvt_pk_bf16_f32 v64, v76, v77
	v_lshl_add_u64 v[68:69], v[208:209], 1, s[42:43]
	v_cvt_pk_bf16_f32 v65, v78, v79
	v_cvt_pk_bf16_f32 v66, v72, v73
	v_cvt_pk_bf16_f32 v67, v74, v75
	global_store_dwordx4 v[68:69], v[64:67], off sc1
	v_lshlrev_b32_e32 v68, 16, v64
	s_nop 0
	v_and_b32_e32 v64, 0xffff0000, v64
	v_mul_f32_e32 v64, v64, v64
	v_fmac_f32_e32 v64, v68, v68
	v_lshlrev_b32_e32 v68, 16, v65
	v_and_b32_e32 v65, 0xffff0000, v65
	v_mul_f32_e32 v65, v65, v65
	v_fmac_f32_e32 v65, v68, v68
	v_add_f32_e32 v64, v64, v65
	v_lshlrev_b32_e32 v65, 16, v66
	v_and_b32_e32 v66, 0xffff0000, v66
	v_mul_f32_e32 v66, v66, v66
	v_fmac_f32_e32 v66, v65, v65
	v_add_f32_e32 v64, v64, v66
	v_and_b32_e32 v66, 0xffff0000, v67
	v_lshlrev_b32_e32 v65, 16, v67
	v_mul_f32_e32 v66, v66, v66
	v_fmac_f32_e32 v66, v65, v65
	v_add_f32_e32 v64, v64, v66
	v_cvt_pk_bf16_f32 v66, v80, v81
	v_cvt_pk_bf16_f32 v67, v70, v71
	v_cvt_pk_bf16_f32 v68, v82, v83
	v_cvt_pk_bf16_f32 v69, v84, v85
	s_nop 0
	v_and_b32_e32 v70, 0xffff0000, v66
	v_lshlrev_b32_e32 v65, 16, v66
	v_mul_f32_e32 v70, v70, v70
	v_fmac_f32_e32 v70, v65, v65
	v_add_f32_e32 v64, v64, v70
	v_and_b32_e32 v70, 0xffff0000, v67
	v_lshlrev_b32_e32 v65, 16, v67
	v_mul_f32_e32 v70, v70, v70
	v_fmac_f32_e32 v70, v65, v65
	v_add_f32_e32 v64, v64, v70
	v_and_b32_e32 v70, 0xffff0000, v68
	v_lshlrev_b32_e32 v65, 16, v68
	v_mul_f32_e32 v70, v70, v70
	v_fmac_f32_e32 v70, v65, v65
	v_add_f32_e32 v64, v64, v70
	v_and_b32_e32 v70, 0xffff0000, v69
	v_lshlrev_b32_e32 v65, 16, v69
	v_mul_f32_e32 v70, v70, v70
	v_fmac_f32_e32 v70, v65, v65
	v_add_f32_e32 v64, v64, v70
	ds_bpermute_b32 v65, v173, v64
	v_lshl_add_u64 v[70:71], v[204:205], 1, s[42:43]
	global_store_dwordx4 v[70:71], v[66:69], off sc1
	s_waitcnt lgkmcnt(0)
	v_add_f32_e32 v64, v64, v65
	ds_bpermute_b32 v65, v220, v64
	s_and_saveexec_b64 s[10:11], vcc
	s_cbranch_execz .LBB0_284
	s_waitcnt lgkmcnt(0)
	v_add_f32_e32 v64, v64, v65
	v_mul_f32_e32 v64, 0x49800000, v64
	v_trunc_f32_e32 v64, v64
	v_mul_f32_e32 v65, 0x2f800000, v64
	v_floor_f32_e32 v65, v65
	v_fmac_f32_e32 v64, 0xcf800000, v65
	v_cvt_u32_f32_e32 v64, v64
	v_cvt_u32_f32_e32 v65, v65
	global_atomic_add_x2 v[218:219], v[64:65], off offset:384
.LBB0_284:
	s_or_b64 exec, exec, s[10:11]
	v_lshlrev_b32_e32 v64, 16, v144
	v_add_f32_e32 v60, v60, v64
	v_and_b32_e32 v64, 0xffff0000, v144
	v_add_f32_e32 v61, v61, v64
	v_lshlrev_b32_e32 v64, 16, v145
	v_add_f32_e32 v62, v62, v64
	v_and_b32_e32 v64, 0xffff0000, v145
	v_add_f32_e32 v63, v63, v64
	v_lshlrev_b32_e32 v64, 16, v146
	v_add_f32_e32 v56, v56, v64
	v_and_b32_e32 v64, 0xffff0000, v146
	v_add_f32_e32 v57, v57, v64
	v_lshlrev_b32_e32 v64, 16, v147
	v_add_f32_e32 v58, v58, v64
	v_and_b32_e32 v64, 0xffff0000, v147
	v_add_f32_e32 v59, v59, v64
	v_lshlrev_b32_e32 v64, 16, v148
	v_add_f32_e32 v64, v52, v64
	v_and_b32_e32 v52, 0xffff0000, v148
	s_waitcnt lgkmcnt(0)
	v_add_f32_e32 v65, v53, v52
	v_lshlrev_b32_e32 v52, 16, v149
	v_add_f32_e32 v54, v54, v52
	v_and_b32_e32 v52, 0xffff0000, v149
	v_add_f32_e32 v55, v55, v52
	v_lshlrev_b32_e32 v52, 16, v150
	v_add_f32_e32 v66, v48, v52
	v_and_b32_e32 v48, 0xffff0000, v150
	v_add_f32_e32 v67, v49, v48
	v_lshlrev_b32_e32 v48, 16, v151
	v_add_f32_e32 v68, v50, v48
	v_and_b32_e32 v48, 0xffff0000, v151
	v_add_f32_e32 v69, v51, v48
	v_cvt_pk_bf16_f32 v48, v60, v61
	v_lshl_add_u64 v[52:53], v[202:203], 1, s[42:43]
	v_cvt_pk_bf16_f32 v49, v62, v63
	v_cvt_pk_bf16_f32 v50, v56, v57
	v_cvt_pk_bf16_f32 v51, v58, v59
	global_store_dwordx4 v[52:53], v[48:51], off sc1
	v_lshlrev_b32_e32 v52, 16, v48
	s_nop 0
	v_and_b32_e32 v48, 0xffff0000, v48
	v_mul_f32_e32 v48, v48, v48
	v_fmac_f32_e32 v48, v52, v52
	v_lshlrev_b32_e32 v52, 16, v49
	v_and_b32_e32 v49, 0xffff0000, v49
	v_mul_f32_e32 v49, v49, v49
	v_fmac_f32_e32 v49, v52, v52
	v_add_f32_e32 v48, v48, v49
	v_lshlrev_b32_e32 v49, 16, v50
	v_and_b32_e32 v50, 0xffff0000, v50
	v_mul_f32_e32 v50, v50, v50
	v_fmac_f32_e32 v50, v49, v49
	v_add_f32_e32 v48, v48, v50
	v_and_b32_e32 v50, 0xffff0000, v51
	v_lshlrev_b32_e32 v49, 16, v51
	v_mul_f32_e32 v50, v50, v50
	v_fmac_f32_e32 v50, v49, v49
	v_add_f32_e32 v48, v48, v50
	v_cvt_pk_bf16_f32 v50, v64, v65
	v_cvt_pk_bf16_f32 v51, v54, v55
	v_cvt_pk_bf16_f32 v52, v66, v67
	v_cvt_pk_bf16_f32 v53, v68, v69
	s_nop 0
	v_and_b32_e32 v54, 0xffff0000, v50
	v_lshlrev_b32_e32 v49, 16, v50
	v_mul_f32_e32 v54, v54, v54
	v_fmac_f32_e32 v54, v49, v49
	v_add_f32_e32 v48, v48, v54
	v_and_b32_e32 v54, 0xffff0000, v51
	v_lshlrev_b32_e32 v49, 16, v51
	v_mul_f32_e32 v54, v54, v54
	v_fmac_f32_e32 v54, v49, v49
	v_add_f32_e32 v48, v48, v54
	v_and_b32_e32 v54, 0xffff0000, v52
	v_lshlrev_b32_e32 v49, 16, v52
	v_mul_f32_e32 v54, v54, v54
	v_fmac_f32_e32 v54, v49, v49
	v_add_f32_e32 v48, v48, v54
	v_and_b32_e32 v54, 0xffff0000, v53
	v_lshlrev_b32_e32 v49, 16, v53
	v_mul_f32_e32 v54, v54, v54
	v_fmac_f32_e32 v54, v49, v49
	v_add_f32_e32 v48, v48, v54
	ds_bpermute_b32 v49, v173, v48
	v_lshl_add_u64 v[54:55], v[210:211], 1, s[42:43]
	global_store_dwordx4 v[54:55], v[50:53], off sc1
	s_waitcnt lgkmcnt(0)
	v_add_f32_e32 v48, v48, v49
	ds_bpermute_b32 v49, v220, v48
	s_and_saveexec_b64 s[10:11], vcc
	s_cbranch_execz .LBB0_286
	s_waitcnt lgkmcnt(0)
	v_add_f32_e32 v48, v48, v49
	v_mul_f32_e32 v48, 0x49800000, v48
	v_trunc_f32_e32 v48, v48
	v_mul_f32_e32 v49, 0x2f800000, v48
	v_floor_f32_e32 v49, v49
	v_fmac_f32_e32 v48, 0xcf800000, v49
	v_cvt_u32_f32_e32 v48, v48
	v_cvt_u32_f32_e32 v49, v49
	global_atomic_add_x2 v[218:219], v[48:49], off offset:1024
.LBB0_286:
	s_or_b64 exec, exec, s[10:11]
	v_lshlrev_b32_e32 v48, 16, v124
	v_add_f32_e32 v44, v44, v48
	v_and_b32_e32 v48, 0xffff0000, v124
	v_add_f32_e32 v45, v45, v48
	v_lshlrev_b32_e32 v48, 16, v125
	v_add_f32_e32 v46, v46, v48
	v_and_b32_e32 v48, 0xffff0000, v125
	v_add_f32_e32 v47, v47, v48
	v_lshlrev_b32_e32 v48, 16, v126
	v_add_f32_e32 v40, v40, v48
	v_and_b32_e32 v48, 0xffff0000, v126
	v_add_f32_e32 v41, v41, v48
	v_lshlrev_b32_e32 v48, 16, v127
	v_add_f32_e32 v42, v42, v48
	v_and_b32_e32 v48, 0xffff0000, v127
	v_add_f32_e32 v43, v43, v48
	v_lshlrev_b32_e32 v48, 16, v128
	v_add_f32_e32 v48, v36, v48
	v_and_b32_e32 v36, 0xffff0000, v128
	s_waitcnt lgkmcnt(0)
	v_add_f32_e32 v49, v37, v36
	v_lshlrev_b32_e32 v36, 16, v129
	v_add_f32_e32 v38, v38, v36
	v_and_b32_e32 v36, 0xffff0000, v129
	v_add_f32_e32 v39, v39, v36
	v_lshlrev_b32_e32 v36, 16, v130
	v_add_f32_e32 v50, v32, v36
	v_and_b32_e32 v32, 0xffff0000, v130
	v_add_f32_e32 v51, v33, v32
	v_lshlrev_b32_e32 v32, 16, v131
	v_add_f32_e32 v52, v34, v32
	v_and_b32_e32 v32, 0xffff0000, v131
	v_add_f32_e32 v53, v35, v32
	v_cvt_pk_bf16_f32 v32, v44, v45
	v_lshl_add_u64 v[36:37], v[206:207], 1, s[42:43]
	v_cvt_pk_bf16_f32 v33, v46, v47
	v_cvt_pk_bf16_f32 v34, v40, v41
	v_cvt_pk_bf16_f32 v35, v42, v43
	global_store_dwordx4 v[36:37], v[32:35], off sc1
	v_lshlrev_b32_e32 v36, 16, v32
	s_nop 0
	v_and_b32_e32 v32, 0xffff0000, v32
	v_mul_f32_e32 v32, v32, v32
	v_fmac_f32_e32 v32, v36, v36
	v_lshlrev_b32_e32 v36, 16, v33
	v_and_b32_e32 v33, 0xffff0000, v33
	v_mul_f32_e32 v33, v33, v33
	v_fmac_f32_e32 v33, v36, v36
	v_add_f32_e32 v32, v32, v33
	v_lshlrev_b32_e32 v33, 16, v34
	v_and_b32_e32 v34, 0xffff0000, v34
	v_mul_f32_e32 v34, v34, v34
	v_fmac_f32_e32 v34, v33, v33
	v_add_f32_e32 v32, v32, v34
	v_and_b32_e32 v34, 0xffff0000, v35
	v_lshlrev_b32_e32 v33, 16, v35
	v_mul_f32_e32 v34, v34, v34
	v_fmac_f32_e32 v34, v33, v33
	v_add_f32_e32 v32, v32, v34
	v_cvt_pk_bf16_f32 v34, v48, v49
	v_cvt_pk_bf16_f32 v35, v38, v39
	v_cvt_pk_bf16_f32 v36, v50, v51
	v_cvt_pk_bf16_f32 v37, v52, v53
	s_nop 0
	v_and_b32_e32 v38, 0xffff0000, v34
	v_lshlrev_b32_e32 v33, 16, v34
	v_mul_f32_e32 v38, v38, v38
	v_fmac_f32_e32 v38, v33, v33
	v_add_f32_e32 v32, v32, v38
	v_and_b32_e32 v38, 0xffff0000, v35
	v_lshlrev_b32_e32 v33, 16, v35
	v_mul_f32_e32 v38, v38, v38
	v_fmac_f32_e32 v38, v33, v33
	v_add_f32_e32 v32, v32, v38
	v_and_b32_e32 v38, 0xffff0000, v36
	v_lshlrev_b32_e32 v33, 16, v36
	v_mul_f32_e32 v38, v38, v38
	v_fmac_f32_e32 v38, v33, v33
	v_add_f32_e32 v32, v32, v38
	v_and_b32_e32 v38, 0xffff0000, v37
	v_lshlrev_b32_e32 v33, 16, v37
	v_mul_f32_e32 v38, v38, v38
	v_fmac_f32_e32 v38, v33, v33
	v_add_f32_e32 v32, v32, v38
	ds_bpermute_b32 v33, v173, v32
	v_lshl_add_u64 v[38:39], v[200:201], 1, s[42:43]
	global_store_dwordx4 v[38:39], v[34:37], off sc1
	s_waitcnt lgkmcnt(0)
	v_add_f32_e32 v32, v32, v33
	ds_bpermute_b32 v33, v220, v32
	s_and_saveexec_b64 s[10:11], vcc
	s_cbranch_execz .LBB0_288
	s_waitcnt lgkmcnt(0)
	v_add_f32_e32 v32, v32, v33
	v_mul_f32_e32 v32, 0x49800000, v32
	v_trunc_f32_e32 v32, v32
	v_mul_f32_e32 v33, 0x2f800000, v32
	v_floor_f32_e32 v33, v33
	v_fmac_f32_e32 v32, 0xcf800000, v33
	v_cvt_u32_f32_e32 v32, v32
	v_cvt_u32_f32_e32 v33, v33
	global_atomic_add_x2 v[218:219], v[32:33], off offset:1152
.LBB0_288:
	s_or_b64 exec, exec, s[10:11]
	s_waitcnt vmcnt(15)
	v_lshlrev_b32_e32 v32, 16, v116
	v_add_f32_e32 v28, v28, v32
	v_and_b32_e32 v32, 0xffff0000, v116
	v_add_f32_e32 v29, v29, v32
	v_lshlrev_b32_e32 v32, 16, v117
	v_add_f32_e32 v30, v30, v32
	v_and_b32_e32 v32, 0xffff0000, v117
	v_add_f32_e32 v31, v31, v32
	v_lshlrev_b32_e32 v32, 16, v118
	v_add_f32_e32 v24, v24, v32
	v_and_b32_e32 v32, 0xffff0000, v118
	v_add_f32_e32 v25, v25, v32
	v_lshlrev_b32_e32 v32, 16, v119
	v_add_f32_e32 v26, v26, v32
	v_and_b32_e32 v32, 0xffff0000, v119
	v_add_f32_e32 v27, v27, v32
	s_waitcnt vmcnt(14)
	v_lshlrev_b32_e32 v32, 16, v120
	v_add_f32_e32 v32, v20, v32
	v_and_b32_e32 v20, 0xffff0000, v120
	s_waitcnt lgkmcnt(0)
	v_add_f32_e32 v33, v21, v20
	v_lshlrev_b32_e32 v20, 16, v121
	v_add_f32_e32 v22, v22, v20
	v_and_b32_e32 v20, 0xffff0000, v121
	v_add_f32_e32 v23, v23, v20
	v_lshlrev_b32_e32 v20, 16, v122
	v_add_f32_e32 v34, v16, v20
	v_and_b32_e32 v16, 0xffff0000, v122
	v_add_f32_e32 v35, v17, v16
	v_lshlrev_b32_e32 v16, 16, v123
	v_add_f32_e32 v36, v18, v16
	v_and_b32_e32 v16, 0xffff0000, v123
	v_add_f32_e32 v37, v19, v16
	v_cvt_pk_bf16_f32 v16, v28, v29
	v_lshl_add_u64 v[20:21], v[198:199], 1, s[42:43]
	v_cvt_pk_bf16_f32 v17, v30, v31
	v_cvt_pk_bf16_f32 v18, v24, v25
	v_cvt_pk_bf16_f32 v19, v26, v27
	global_store_dwordx4 v[20:21], v[16:19], off sc1
	v_lshlrev_b32_e32 v20, 16, v16
	s_nop 0
	v_and_b32_e32 v16, 0xffff0000, v16
	v_mul_f32_e32 v16, v16, v16
	v_fmac_f32_e32 v16, v20, v20
	v_lshlrev_b32_e32 v20, 16, v17
	v_and_b32_e32 v17, 0xffff0000, v17
	v_mul_f32_e32 v17, v17, v17
	v_fmac_f32_e32 v17, v20, v20
	v_add_f32_e32 v16, v16, v17
	v_lshlrev_b32_e32 v17, 16, v18
	v_and_b32_e32 v18, 0xffff0000, v18
	v_mul_f32_e32 v18, v18, v18
	v_fmac_f32_e32 v18, v17, v17
	v_add_f32_e32 v16, v16, v18
	v_and_b32_e32 v18, 0xffff0000, v19
	v_lshlrev_b32_e32 v17, 16, v19
	v_mul_f32_e32 v18, v18, v18
	v_fmac_f32_e32 v18, v17, v17
	v_add_f32_e32 v16, v16, v18
	v_cvt_pk_bf16_f32 v18, v32, v33
	v_cvt_pk_bf16_f32 v19, v22, v23
	v_cvt_pk_bf16_f32 v20, v34, v35
	v_cvt_pk_bf16_f32 v21, v36, v37
	s_nop 0
	v_and_b32_e32 v22, 0xffff0000, v18
	v_lshlrev_b32_e32 v17, 16, v18
	v_mul_f32_e32 v22, v22, v22
	v_fmac_f32_e32 v22, v17, v17
	v_add_f32_e32 v16, v16, v22
	v_and_b32_e32 v22, 0xffff0000, v19
	v_lshlrev_b32_e32 v17, 16, v19
	v_mul_f32_e32 v22, v22, v22
	v_fmac_f32_e32 v22, v17, v17
	v_add_f32_e32 v16, v16, v22
	v_and_b32_e32 v22, 0xffff0000, v20
	v_lshlrev_b32_e32 v17, 16, v20
	v_mul_f32_e32 v22, v22, v22
	v_fmac_f32_e32 v22, v17, v17
	v_add_f32_e32 v16, v16, v22
	v_and_b32_e32 v22, 0xffff0000, v21
	v_lshlrev_b32_e32 v17, 16, v21
	v_mul_f32_e32 v22, v22, v22
	v_fmac_f32_e32 v22, v17, v17
	v_add_f32_e32 v16, v16, v22
	ds_bpermute_b32 v17, v173, v16
	v_lshl_add_u64 v[22:23], v[196:197], 1, s[42:43]
	global_store_dwordx4 v[22:23], v[18:21], off sc1
	s_waitcnt lgkmcnt(0)
	v_add_f32_e32 v16, v16, v17
	ds_bpermute_b32 v17, v220, v16
	s_and_saveexec_b64 s[10:11], vcc
	s_cbranch_execz .LBB0_290
	s_waitcnt lgkmcnt(0)
	v_add_f32_e32 v16, v16, v17
	v_mul_f32_e32 v16, 0x49800000, v16
	v_trunc_f32_e32 v16, v16
	v_mul_f32_e32 v17, 0x2f800000, v16
	v_floor_f32_e32 v17, v17
	v_fmac_f32_e32 v16, 0xcf800000, v17
	v_cvt_u32_f32_e32 v16, v16
	v_cvt_u32_f32_e32 v17, v17
	global_atomic_add_x2 v[218:219], v[16:17], off offset:1280
.LBB0_290:
	s_or_b64 exec, exec, s[10:11]
	s_waitcnt vmcnt(15)
	v_lshlrev_b32_e32 v16, 16, v112
	v_add_f32_e32 v12, v12, v16
	v_and_b32_e32 v16, 0xffff0000, v112
	v_add_f32_e32 v13, v13, v16
	v_lshlrev_b32_e32 v16, 16, v113
	v_add_f32_e32 v14, v14, v16
	v_and_b32_e32 v16, 0xffff0000, v113
	v_add_f32_e32 v15, v15, v16
	v_lshlrev_b32_e32 v16, 16, v114
	v_add_f32_e32 v8, v8, v16
	v_and_b32_e32 v16, 0xffff0000, v114
	v_add_f32_e32 v9, v9, v16
	v_lshlrev_b32_e32 v16, 16, v115
	v_add_f32_e32 v10, v10, v16
	v_and_b32_e32 v16, 0xffff0000, v115
	v_add_f32_e32 v11, v11, v16
	s_waitcnt vmcnt(14)
	v_lshlrev_b32_e32 v16, 16, v140
	v_add_f32_e32 v16, v4, v16
	v_and_b32_e32 v4, 0xffff0000, v140
	s_waitcnt lgkmcnt(0)
	v_add_f32_e32 v17, v5, v4
	v_lshlrev_b32_e32 v4, 16, v141
	v_add_f32_e32 v6, v6, v4
	v_and_b32_e32 v4, 0xffff0000, v141
	v_add_f32_e32 v7, v7, v4
	v_lshlrev_b32_e32 v4, 16, v142
	v_add_f32_e32 v18, v0, v4
	v_and_b32_e32 v0, 0xffff0000, v142
	v_add_f32_e32 v19, v1, v0
	v_lshlrev_b32_e32 v0, 16, v143
	v_add_f32_e32 v20, v2, v0
	v_and_b32_e32 v0, 0xffff0000, v143
	v_add_f32_e32 v21, v3, v0
	v_cvt_pk_bf16_f32 v0, v12, v13
	v_lshl_add_u64 v[4:5], v[194:195], 1, s[42:43]
	v_cvt_pk_bf16_f32 v1, v14, v15
	v_cvt_pk_bf16_f32 v2, v8, v9
	v_cvt_pk_bf16_f32 v3, v10, v11
	global_store_dwordx4 v[4:5], v[0:3], off sc1
	v_lshlrev_b32_e32 v4, 16, v0
	s_nop 0
	v_and_b32_e32 v0, 0xffff0000, v0
	v_mul_f32_e32 v0, v0, v0
	v_fmac_f32_e32 v0, v4, v4
	v_lshlrev_b32_e32 v4, 16, v1
	v_and_b32_e32 v1, 0xffff0000, v1
	v_mul_f32_e32 v1, v1, v1
	v_fmac_f32_e32 v1, v4, v4
	v_add_f32_e32 v0, v0, v1
	v_lshlrev_b32_e32 v1, 16, v2
	v_and_b32_e32 v2, 0xffff0000, v2
	v_mul_f32_e32 v2, v2, v2
	v_fmac_f32_e32 v2, v1, v1
	v_add_f32_e32 v0, v0, v2
	v_and_b32_e32 v2, 0xffff0000, v3
	v_lshlrev_b32_e32 v1, 16, v3
	v_mul_f32_e32 v2, v2, v2
	v_fmac_f32_e32 v2, v1, v1
	v_add_f32_e32 v0, v0, v2
	v_cvt_pk_bf16_f32 v2, v16, v17
	v_cvt_pk_bf16_f32 v3, v6, v7
	v_cvt_pk_bf16_f32 v4, v18, v19
	v_cvt_pk_bf16_f32 v5, v20, v21
	s_nop 0
	v_and_b32_e32 v6, 0xffff0000, v2
	v_lshlrev_b32_e32 v1, 16, v2
	v_mul_f32_e32 v6, v6, v6
	v_fmac_f32_e32 v6, v1, v1
	v_add_f32_e32 v0, v0, v6
	v_and_b32_e32 v6, 0xffff0000, v3
	v_lshlrev_b32_e32 v1, 16, v3
	v_mul_f32_e32 v6, v6, v6
	v_fmac_f32_e32 v6, v1, v1
	v_add_f32_e32 v0, v0, v6
	v_and_b32_e32 v6, 0xffff0000, v4
	v_lshlrev_b32_e32 v1, 16, v4
	v_mul_f32_e32 v6, v6, v6
	v_fmac_f32_e32 v6, v1, v1
	v_add_f32_e32 v0, v0, v6
	v_and_b32_e32 v6, 0xffff0000, v5
	v_lshlrev_b32_e32 v1, 16, v5
	v_mul_f32_e32 v6, v6, v6
	v_fmac_f32_e32 v6, v1, v1
	v_add_f32_e32 v0, v0, v6
	ds_bpermute_b32 v1, v173, v0
	v_lshl_add_u64 v[6:7], v[192:193], 1, s[42:43]
	global_store_dwordx4 v[6:7], v[2:5], off sc1
	s_waitcnt lgkmcnt(0)
	v_add_f32_e32 v0, v0, v1
	ds_bpermute_b32 v1, v220, v0
	s_and_saveexec_b64 s[10:11], vcc
	s_cbranch_execz .LBB0_265
	s_waitcnt lgkmcnt(0)
	v_add_f32_e32 v0, v0, v1
	v_mul_f32_e32 v0, 0x49800000, v0
	v_trunc_f32_e32 v0, v0
	v_mul_f32_e32 v1, 0x2f800000, v0
	v_floor_f32_e32 v1, v1
	v_fmac_f32_e32 v0, 0xcf800000, v1
	v_cvt_u32_f32_e32 v0, v0
	v_cvt_u32_f32_e32 v1, v1
	global_atomic_add_x2 v[218:219], v[0:1], off offset:1408
	s_branch .LBB0_265
